# static s_setprio 1 for waves 4-7 at kernel entry, all per-segment setprio toggles removed from the GEMM K-loops
# baseline (speedup 1.0000x reference)
; #define LAS __attribute__((address_space(3)))
; __global__ void __launch_bounds__(512, 2) fwd(Args a) {
;     extern __shared__ __attribute__((aligned(16))) unsigned char lds_raw[];
;     LAS unsigned char* lds = (LAS unsigned char*)lds_raw;
;     cg::grid_group grid = cg::this_grid();
;     const int G = gridDim.x;
;     const int vcu0 = (G % 8 == 0) ? ((int)blockIdx.x % 8) * (G / 8) + (int)blockIdx.x / 8 : (int)blockIdx.x;
_Z3fwd4Args:
	s_load_dwordx2 s[72:73], s[0:1], 0xb8
	s_mov_b64 s[56:57], s[0:1]
	s_add_u32 s0, s56, 0xb8
	s_addc_u32 s1, s57, 0
	v_writelane_b32 v252, s2, 0
	v_readfirstlane_b32 s98, v0
	s_bitcmp1_b32 s98, 8
	s_cbranch_scc0 .Lprio_skip
	s_setprio 1
.Lprio_skip:
	s_waitcnt lgkmcnt(0)
	s_and_b32 s4, s72, 7
	s_cmp_lg_u32 s4, 0
	s_cbranch_scc1 .LBB0_2
	v_readlane_b32 s2, v252, 0
	s_ashr_i32 s5, s2, 31
	s_lshr_b32 s5, s5, 29
	s_add_i32 s5, s2, s5
	s_ashr_i32 s6, s5, 3
	s_and_b32 s5, s5, -8
	s_ashr_i32 s4, s72, 3
	s_sub_i32 s5, s2, s5
	s_mul_i32 s4, s4, s5
	s_add_i32 s2, s4, s6

; #define PG8_STAGE(bufoff, gbase, voff) do { _Pragma("unroll") for (int _i = 0; _i < 2; ++_i) \
;         __builtin_amdgcn_global_load_lds((const unsigned*)((const char*)(gbase) + (voff)[_i]), (PG8_LAS unsigned*)(lds + (bufoff) + ldsw + _i * 8192), 16, 0, 0); } while (0)
; #define PG8_LDA(dst, b, h) do { _Pragma("unroll") for (int m = 0; m < 4; ++m) _Pragma("unroll") for (int k = 0; k < 2; ++k) dst[m][k] = *(const PG8_LAS bf16x8*)(lds + PG8_SA(b, h) + aoff + m * 2048 + k * 1024); } while (0)
; #define PG8_LDB(dst, b, h) do { _Pragma("unroll") for (int n = 0; n < 2; ++n) _Pragma("unroll") for (int k = 0; k < 2; ++k) dst[n][k] = *(const PG8_LAS bf16x8*)(lds + PG8_SB(b, h) + boff + n * 2048 + k * 1024); } while (0)
; #define PG8_MMA(ai, bj, At, Bt) do { __builtin_amdgcn_s_setprio(1); _Pragma("unroll") for (int m = 0; m < 4; ++m) _Pragma("unroll") for (int n = 0; n < 2; ++n) _Pragma("unroll") for (int k = 0; k < 2; ++k) \
;         acc[ai][bj][m][n] = __builtin_amdgcn_mfma_f32_16x16x32_bf16(Bt[n][k], At[m][k], acc[ai][bj][m][n], 0, 0, 0); __builtin_amdgcn_s_setprio(0); } while (0)
; #define PG8_WAIT_V(n) asm volatile("s_waitcnt vmcnt(" #n ")" ::: "memory")
; #define PG8_WAIT_L(n) asm volatile("s_waitcnt lgkmcnt(" #n ")" ::: "memory")
; #define PG8_BAR __builtin_amdgcn_s_barrier()
; #define PG8_SCHED __builtin_amdgcn_sched_barrier(0)
; template <class Epi, class Sched, bool ALIGN_EPI = false, bool SP2 = false, bool HALFM = false>
; __device__ __forceinline__ void gemm_phase(PG8_LAS unsigned char* lds, const Gemm g, const Sched& S, const Epi& E) {
;     ...
;             PG8_LDB(B0, 0, 0); PG8_LDB(B1, 0, 1); PG8_SCHED; PG8_LDA(At, 0, 0); PG8_STAGE(PG8_SA(1, 1), a1 + hstep, voffA);
;             PG8_WAIT_V(8); PG8_WAIT_L(0); PG8_BAR; PG8_MMA(0, 0, At, B0); PG8_MMA(0, 1, At, B1); PG8_BAR; PG8_SCHED;
;             if constexpr (!HALFM) PG8_LDA(At, 0, 1); PG8_STAGE(PG8_SB(0, 0), b2, voffB); PG8_STAGE(PG8_SB(0, 1), b2 + hstep, voffB); PG8_STAGE(PG8_SA(0, 0), a2, voffA);
.LBB0_179:
	s_add_u32 s26, s22, 0xfffc0080
	s_addc_u32 s27, s23, -1
	s_and_b64 s[24:25], s[24:25], exec
	s_cselect_b32 s27, s27, s11
	s_cselect_b32 s26, s26, s58
	s_cselect_b32 s25, s63, s9
	s_cselect_b32 s24, s62, s59
	s_add_i32 s65, 0, 0x10000
	v_add_u32_e32 v140, s65, v143
	s_add_i32 s68, 0, 0x14000
	ds_read_b128 v[148:151], v140
	ds_read_b128 v[160:163], v140 offset:1024
	ds_read_b128 v[164:167], v140 offset:2048
	ds_read_b128 v[168:171], v140 offset:3072
	v_add_u32_e32 v140, s68, v143
	ds_read_b128 v[172:175], v140
	ds_read_b128 v[176:179], v140 offset:1024
	ds_read_b128 v[180:183], v140 offset:2048
	ds_read_b128 v[184:187], v140 offset:3072
	v_lshl_add_u64 v[140:141], s[22:23], 0, v[136:137]
	s_add_i32 m0, s47, 0xc000
	ds_read_b128 v[202:205], v146
	ds_read_b128 v[206:209], v146 offset:1024
	ds_read_b128 v[210:213], v146 offset:2048
	ds_read_b128 v[214:217], v146 offset:3072
	ds_read_b128 v[218:221], v146 offset:4096
	ds_read_b128 v[222:225], v146 offset:5120
	ds_read_b128 v[226:229], v146 offset:6144
	ds_read_b128 v[230:233], v146 offset:7168
	global_load_lds_dwordx4 v[140:141], off
	v_lshl_add_u64 v[140:141], s[22:23], 0, v[138:139]
	s_add_i32 m0, s47, 0xe000
	s_nop 0
	global_load_lds_dwordx4 v[140:141], off
	s_waitcnt vmcnt(8)
	s_waitcnt lgkmcnt(0)
	s_barrier
	v_mfma_f32_16x16x32_bf16 v[126:129], v[148:151], v[202:205], v[126:129]
	v_mfma_f32_16x16x32_bf16 v[122:125], v[164:167], v[202:205], v[122:125]
	v_mfma_f32_16x16x32_bf16 v[110:113], v[148:151], v[210:213], v[110:113]
	v_mfma_f32_16x16x32_bf16 v[106:109], v[164:167], v[210:213], v[106:109]
	v_mfma_f32_16x16x32_bf16 v[94:97], v[148:151], v[218:221], v[94:97]
	v_mfma_f32_16x16x32_bf16 v[90:93], v[164:167], v[218:221], v[90:93]
	v_mfma_f32_16x16x32_bf16 v[76:79], v[148:151], v[226:229], v[76:79]
	v_mfma_f32_16x16x32_bf16 v[72:75], v[164:167], v[226:229], v[72:75]
	v_mfma_f32_16x16x32_bf16 v[126:129], v[160:163], v[206:209], v[126:129]
	v_mfma_f32_16x16x32_bf16 v[122:125], v[168:171], v[206:209], v[122:125]
	v_mfma_f32_16x16x32_bf16 v[110:113], v[160:163], v[214:217], v[110:113]
	v_mfma_f32_16x16x32_bf16 v[106:109], v[168:171], v[214:217], v[106:109]
	v_mfma_f32_16x16x32_bf16 v[94:97], v[160:163], v[222:225], v[94:97]
	v_mfma_f32_16x16x32_bf16 v[90:93], v[168:171], v[222:225], v[90:93]
	v_mfma_f32_16x16x32_bf16 v[76:79], v[160:163], v[230:233], v[76:79]
	v_mfma_f32_16x16x32_bf16 v[72:75], v[168:171], v[230:233], v[72:75]
	v_mfma_f32_16x16x32_bf16 v[118:121], v[172:175], v[202:205], v[118:121]
	v_mfma_f32_16x16x32_bf16 v[114:117], v[180:183], v[202:205], v[114:117]
	v_mfma_f32_16x16x32_bf16 v[102:105], v[172:175], v[210:213], v[102:105]
	v_mfma_f32_16x16x32_bf16 v[98:101], v[180:183], v[210:213], v[98:101]
	v_mfma_f32_16x16x32_bf16 v[86:89], v[172:175], v[218:221], v[86:89]
	v_mfma_f32_16x16x32_bf16 v[82:85], v[180:183], v[218:221], v[82:85]
	v_mfma_f32_16x16x32_bf16 v[68:71], v[172:175], v[226:229], v[68:71]
	v_mfma_f32_16x16x32_bf16 v[64:67], v[180:183], v[226:229], v[64:67]
	v_mfma_f32_16x16x32_bf16 v[118:121], v[176:179], v[206:209], v[118:121]
	v_mfma_f32_16x16x32_bf16 v[114:117], v[184:187], v[206:209], v[114:117]
	v_mfma_f32_16x16x32_bf16 v[102:105], v[176:179], v[214:217], v[102:105]
	v_mfma_f32_16x16x32_bf16 v[98:101], v[184:187], v[214:217], v[98:101]
	v_mfma_f32_16x16x32_bf16 v[86:89], v[176:179], v[222:225], v[86:89]
	v_mfma_f32_16x16x32_bf16 v[82:85], v[184:187], v[222:225], v[82:85]
	v_mfma_f32_16x16x32_bf16 v[68:71], v[176:179], v[230:233], v[68:71]
	v_mfma_f32_16x16x32_bf16 v[64:67], v[184:187], v[230:233], v[64:67]
	s_barrier
	s_add_i32 s65, s65, s46
	v_lshl_add_u64 v[140:141], s[24:25], 0, v[80:81]
	s_mov_b32 m0, s65
	ds_read_b128 v[202:205], v146 offset:16384
	ds_read_b128 v[206:209], v146 offset:17408
	ds_read_b128 v[210:213], v146 offset:18432
	ds_read_b128 v[214:217], v146 offset:19456
	ds_read_b128 v[218:221], v146 offset:20480
	ds_read_b128 v[222:225], v146 offset:21504
	ds_read_b128 v[226:229], v146 offset:22528
	ds_read_b128 v[230:233], v146 offset:23552
	global_load_lds_dwordx4 v[140:141], off
	s_add_i32 m0, s65, 0x2000
	s_add_u32 s66, s24, 0x40000
	v_lshl_add_u64 v[152:153], s[24:25], 0, v[134:135]
	s_addc_u32 s67, s25, 0
	s_add_i32 s65, s68, s46
	global_load_lds_dwordx4 v[152:153], off
	v_lshl_add_u64 v[188:189], s[66:67], 0, v[80:81]
	s_mov_b32 m0, s65
	v_lshl_add_u64 v[196:197], s[26:27], 0, v[132:133]
	global_load_lds_dwordx4 v[188:189], off
	v_lshl_add_u64 v[188:189], s[66:67], 0, v[134:135]
	s_add_i32 m0, s65, 0x2000
	s_nop 0
	global_load_lds_dwordx4 v[188:189], off
	v_lshl_add_u64 v[188:189], s[26:27], 0, v[130:131]
	s_mov_b32 m0, s47
	s_nop 0
	global_load_lds_dwordx4 v[188:189], off
	s_mov_b32 m0, s48
	s_nop 0
	global_load_lds_dwordx4 v[196:197], off
	s_waitcnt vmcnt(8)
	s_waitcnt lgkmcnt(0)
	s_barrier
; #define PG8_STAGE(bufoff, gbase, voff) do { _Pragma("unroll") for (int _i = 0; _i < 2; ++_i) \
;         __builtin_amdgcn_global_load_lds((const unsigned*)((const char*)(gbase) + (voff)[_i]), (PG8_LAS unsigned*)(lds + (bufoff) + ldsw + _i * 8192), 16, 0, 0); } while (0)
; #define PG8_LDA(dst, b, h) do { _Pragma("unroll") for (int m = 0; m < 4; ++m) _Pragma("unroll") for (int k = 0; k < 2; ++k) dst[m][k] = *(const PG8_LAS bf16x8*)(lds + PG8_SA(b, h) + aoff + m * 2048 + k * 1024); } while (0)
; #define PG8_LDB(dst, b, h) do { _Pragma("unroll") for (int n = 0; n < 2; ++n) _Pragma("unroll") for (int k = 0; k < 2; ++k) dst[n][k] = *(const PG8_LAS bf16x8*)(lds + PG8_SB(b, h) + boff + n * 2048 + k * 1024); } while (0)
; #define PG8_MMA(ai, bj, At, Bt) do { __builtin_amdgcn_s_setprio(1); _Pragma("unroll") for (int m = 0; m < 4; ++m) _Pragma("unroll") for (int n = 0; n < 2; ++n) _Pragma("unroll") for (int k = 0; k < 2; ++k) \
;         acc[ai][bj][m][n] = __builtin_amdgcn_mfma_f32_16x16x32_bf16(Bt[n][k], At[m][k], acc[ai][bj][m][n], 0, 0, 0); __builtin_amdgcn_s_setprio(0); } while (0)
; #define PG8_WAIT_V(n) asm volatile("s_waitcnt vmcnt(" #n ")" ::: "memory")
; #define PG8_WAIT_L(n) asm volatile("s_waitcnt lgkmcnt(" #n ")" ::: "memory")
; #define PG8_BAR __builtin_amdgcn_s_barrier()
; #define PG8_SCHED __builtin_amdgcn_sched_barrier(0)
; template <class Epi, class Sched, bool ALIGN_EPI = false, bool SP2 = false, bool HALFM = false>
; __device__ __forceinline__ void gemm_phase(PG8_LAS unsigned char* lds, const Gemm g, const Sched& S, const Epi& E) {
;     ...
;             PG8_WAIT_V(8); PG8_WAIT_L(0); PG8_BAR; if constexpr (!HALFM) { PG8_MMA(1, 0, At, B0); PG8_MMA(1, 1, At, B1); } PG8_BAR; PG8_SCHED;
;             PG8_LDB(B0, 1, 0); PG8_LDB(B1, 1, 1); PG8_SCHED; PG8_LDA(At, 1, 0); PG8_STAGE(PG8_SA(0, 1), a2 + hstep, voffA);
;             PG8_WAIT_V(8); PG8_WAIT_L(0); PG8_BAR; PG8_MMA(0, 0, At, B0); PG8_MMA(0, 1, At, B1); PG8_BAR; PG8_SCHED;
	v_mfma_f32_16x16x32_bf16 v[60:63], v[148:151], v[202:205], v[60:63]
	v_mfma_f32_16x16x32_bf16 v[56:59], v[164:167], v[202:205], v[56:59]
	v_mfma_f32_16x16x32_bf16 v[44:47], v[148:151], v[210:213], v[44:47]
	v_mfma_f32_16x16x32_bf16 v[40:43], v[164:167], v[210:213], v[40:43]
	v_mfma_f32_16x16x32_bf16 v[28:31], v[148:151], v[218:221], v[28:31]
	v_mfma_f32_16x16x32_bf16 v[24:27], v[164:167], v[218:221], v[24:27]
	v_mfma_f32_16x16x32_bf16 v[12:15], v[148:151], v[226:229], v[12:15]
	v_mfma_f32_16x16x32_bf16 v[8:11], v[164:167], v[226:229], v[8:11]
	v_mfma_f32_16x16x32_bf16 v[60:63], v[160:163], v[206:209], v[60:63]
	v_mfma_f32_16x16x32_bf16 v[56:59], v[168:171], v[206:209], v[56:59]
	v_mfma_f32_16x16x32_bf16 v[44:47], v[160:163], v[214:217], v[44:47]
	v_mfma_f32_16x16x32_bf16 v[40:43], v[168:171], v[214:217], v[40:43]
	v_mfma_f32_16x16x32_bf16 v[28:31], v[160:163], v[222:225], v[28:31]
	v_mfma_f32_16x16x32_bf16 v[24:27], v[168:171], v[222:225], v[24:27]
	v_mfma_f32_16x16x32_bf16 v[12:15], v[160:163], v[230:233], v[12:15]
	v_mfma_f32_16x16x32_bf16 v[8:11], v[168:171], v[230:233], v[8:11]
	v_mfma_f32_16x16x32_bf16 v[52:55], v[172:175], v[202:205], v[52:55]
	v_mfma_f32_16x16x32_bf16 v[48:51], v[180:183], v[202:205], v[48:51]
	v_mfma_f32_16x16x32_bf16 v[36:39], v[172:175], v[210:213], v[36:39]
	v_mfma_f32_16x16x32_bf16 v[32:35], v[180:183], v[210:213], v[32:35]
	v_mfma_f32_16x16x32_bf16 v[20:23], v[172:175], v[218:221], v[20:23]
	v_mfma_f32_16x16x32_bf16 v[16:19], v[180:183], v[218:221], v[16:19]
	v_mfma_f32_16x16x32_bf16 v[4:7], v[172:175], v[226:229], v[4:7]
	v_mfma_f32_16x16x32_bf16 v[0:3], v[180:183], v[226:229], v[0:3]
	v_mfma_f32_16x16x32_bf16 v[52:55], v[176:179], v[206:209], v[52:55]
	v_mfma_f32_16x16x32_bf16 v[48:51], v[184:187], v[206:209], v[48:51]
	v_mfma_f32_16x16x32_bf16 v[36:39], v[176:179], v[214:217], v[36:39]
	v_mfma_f32_16x16x32_bf16 v[32:35], v[184:187], v[214:217], v[32:35]
	v_mfma_f32_16x16x32_bf16 v[20:23], v[176:179], v[222:225], v[20:23]
	v_mfma_f32_16x16x32_bf16 v[16:19], v[184:187], v[222:225], v[16:19]
	v_mfma_f32_16x16x32_bf16 v[4:7], v[176:179], v[230:233], v[4:7]
	v_mfma_f32_16x16x32_bf16 v[0:3], v[184:187], v[230:233], v[0:3]
	s_barrier
	s_add_i32 s65, 0, 0x18000
	v_add_u32_e32 v147, s65, v143
	s_add_i32 s66, 0, 0x1c000
	ds_read_b128 v[148:151], v147
	ds_read_b128 v[160:163], v147 offset:1024
	ds_read_b128 v[164:167], v147 offset:2048
	ds_read_b128 v[168:171], v147 offset:3072
	v_add_u32_e32 v147, s66, v143
	ds_read_b128 v[172:175], v147
	ds_read_b128 v[176:179], v147 offset:1024
	ds_read_b128 v[180:183], v147 offset:2048
	ds_read_b128 v[184:187], v147 offset:3072
	s_add_u32 s26, s26, 0x40000
	s_addc_u32 s27, s27, 0
	s_mov_b32 m0, s49
	v_lshl_add_u64 v[198:199], s[26:27], 0, v[130:131]
	ds_read_b128 v[202:205], v146 offset:32768
	ds_read_b128 v[206:209], v146 offset:33792
	ds_read_b128 v[210:213], v146 offset:34816
	ds_read_b128 v[214:217], v146 offset:35840
	ds_read_b128 v[218:221], v146 offset:36864
	ds_read_b128 v[222:225], v146 offset:37888
	ds_read_b128 v[226:229], v146 offset:38912
	ds_read_b128 v[230:233], v146 offset:39936
	global_load_lds_dwordx4 v[198:199], off
	v_lshl_add_u64 v[198:199], s[26:27], 0, v[132:133]
	s_mov_b32 m0, s50
	s_nop 0
	global_load_lds_dwordx4 v[198:199], off
	s_waitcnt vmcnt(8)
	s_waitcnt lgkmcnt(0)
	s_barrier
	v_mfma_f32_16x16x32_bf16 v[126:129], v[148:151], v[202:205], v[126:129]
	v_mfma_f32_16x16x32_bf16 v[122:125], v[164:167], v[202:205], v[122:125]
	v_mfma_f32_16x16x32_bf16 v[110:113], v[148:151], v[210:213], v[110:113]
	v_mfma_f32_16x16x32_bf16 v[106:109], v[164:167], v[210:213], v[106:109]
	v_mfma_f32_16x16x32_bf16 v[94:97], v[148:151], v[218:221], v[94:97]
	v_mfma_f32_16x16x32_bf16 v[90:93], v[164:167], v[218:221], v[90:93]
	v_mfma_f32_16x16x32_bf16 v[76:79], v[148:151], v[226:229], v[76:79]
	v_mfma_f32_16x16x32_bf16 v[72:75], v[164:167], v[226:229], v[72:75]
	v_mfma_f32_16x16x32_bf16 v[126:129], v[160:163], v[206:209], v[126:129]
	v_mfma_f32_16x16x32_bf16 v[122:125], v[168:171], v[206:209], v[122:125]
	v_mfma_f32_16x16x32_bf16 v[110:113], v[160:163], v[214:217], v[110:113]
	v_mfma_f32_16x16x32_bf16 v[106:109], v[168:171], v[214:217], v[106:109]
	v_mfma_f32_16x16x32_bf16 v[94:97], v[160:163], v[222:225], v[94:97]
	v_mfma_f32_16x16x32_bf16 v[90:93], v[168:171], v[222:225], v[90:93]
	v_mfma_f32_16x16x32_bf16 v[76:79], v[160:163], v[230:233], v[76:79]
	v_mfma_f32_16x16x32_bf16 v[72:75], v[168:171], v[230:233], v[72:75]
	v_mfma_f32_16x16x32_bf16 v[118:121], v[172:175], v[202:205], v[118:121]
	v_mfma_f32_16x16x32_bf16 v[114:117], v[180:183], v[202:205], v[114:117]
	v_mfma_f32_16x16x32_bf16 v[102:105], v[172:175], v[210:213], v[102:105]
	v_mfma_f32_16x16x32_bf16 v[98:101], v[180:183], v[210:213], v[98:101]
	v_mfma_f32_16x16x32_bf16 v[86:89], v[172:175], v[218:221], v[86:89]
	v_mfma_f32_16x16x32_bf16 v[82:85], v[180:183], v[218:221], v[82:85]
	v_mfma_f32_16x16x32_bf16 v[68:71], v[172:175], v[226:229], v[68:71]
	v_mfma_f32_16x16x32_bf16 v[64:67], v[180:183], v[226:229], v[64:67]
	v_mfma_f32_16x16x32_bf16 v[118:121], v[176:179], v[206:209], v[118:121]
	v_mfma_f32_16x16x32_bf16 v[114:117], v[184:187], v[206:209], v[114:117]
	v_mfma_f32_16x16x32_bf16 v[102:105], v[176:179], v[214:217], v[102:105]
	v_mfma_f32_16x16x32_bf16 v[98:101], v[184:187], v[214:217], v[98:101]
	v_mfma_f32_16x16x32_bf16 v[86:89], v[176:179], v[222:225], v[86:89]
	v_mfma_f32_16x16x32_bf16 v[82:85], v[184:187], v[222:225], v[82:85]
	v_mfma_f32_16x16x32_bf16 v[68:71], v[176:179], v[230:233], v[68:71]
	v_mfma_f32_16x16x32_bf16 v[64:67], v[184:187], v[230:233], v[64:67]
	s_barrier
; #define PG8_STAGE(bufoff, gbase, voff) do { _Pragma("unroll") for (int _i = 0; _i < 2; ++_i) \
;         __builtin_amdgcn_global_load_lds((const unsigned*)((const char*)(gbase) + (voff)[_i]), (PG8_LAS unsigned*)(lds + (bufoff) + ldsw + _i * 8192), 16, 0, 0); } while (0)
; #define PG8_LDA(dst, b, h) do { _Pragma("unroll") for (int m = 0; m < 4; ++m) _Pragma("unroll") for (int k = 0; k < 2; ++k) dst[m][k] = *(const PG8_LAS bf16x8*)(lds + PG8_SA(b, h) + aoff + m * 2048 + k * 1024); } while (0)
; #define PG8_MMA(ai, bj, At, Bt) do { __builtin_amdgcn_s_setprio(1); _Pragma("unroll") for (int m = 0; m < 4; ++m) _Pragma("unroll") for (int n = 0; n < 2; ++n) _Pragma("unroll") for (int k = 0; k < 2; ++k) \
;         acc[ai][bj][m][n] = __builtin_amdgcn_mfma_f32_16x16x32_bf16(Bt[n][k], At[m][k], acc[ai][bj][m][n], 0, 0, 0); __builtin_amdgcn_s_setprio(0); } while (0)
; #define PG8_WAIT_V(n) asm volatile("s_waitcnt vmcnt(" #n ")" ::: "memory")
; #define PG8_WAIT_L(n) asm volatile("s_waitcnt lgkmcnt(" #n ")" ::: "memory")
; #define PG8_BAR __builtin_amdgcn_s_barrier()
; #define PG8_SCHED __builtin_amdgcn_sched_barrier(0)
; template <class Epi, class Sched, bool ALIGN_EPI = false, bool SP2 = false, bool HALFM = false>
; __device__ __forceinline__ void gemm_phase(PG8_LAS unsigned char* lds, const Gemm g, const Sched& S, const Epi& E) {
;     ...
;         for (int t = 0; t < nt; t += 2) {
;     ...
;             if constexpr (!HALFM) PG8_LDA(At, 1, 1); PG8_STAGE(PG8_SB(1, 0), b3, voffB); PG8_STAGE(PG8_SB(1, 1), b3 + hstep, voffB); PG8_STAGE(PG8_SA(1, 0), a3, voffA);
;             PG8_WAIT_V(8); PG8_WAIT_L(0); PG8_BAR; if constexpr (!HALFM) { PG8_MMA(1, 0, At, B0); PG8_MMA(1, 1, At, B1); } PG8_BAR; PG8_SCHED;
	s_add_i32 s26, s65, s46
	v_lshl_add_u64 v[140:141], v[140:141], 0, s[82:83]
	s_mov_b32 m0, s26
	ds_read_b128 v[202:205], v146 offset:49152
	ds_read_b128 v[206:209], v146 offset:50176
	ds_read_b128 v[210:213], v146 offset:51200
	ds_read_b128 v[214:217], v146 offset:52224
	ds_read_b128 v[218:221], v146 offset:53248
	ds_read_b128 v[222:225], v146 offset:54272
	ds_read_b128 v[226:229], v146 offset:55296
	ds_read_b128 v[230:233], v146 offset:56320
	global_load_lds_dwordx4 v[140:141], off
	s_add_i32 m0, s26, 0x2000
	s_add_u32 s24, s24, 0x40080
	v_lshl_add_u64 v[140:141], v[152:153], 0, s[82:83]
	s_addc_u32 s25, s25, 0
	s_add_i32 s26, s66, s46
	global_load_lds_dwordx4 v[140:141], off
	v_lshl_add_u64 v[140:141], s[24:25], 0, v[80:81]
	s_mov_b32 m0, s26
	s_nop 0
	global_load_lds_dwordx4 v[140:141], off
	v_lshl_add_u64 v[140:141], s[24:25], 0, v[134:135]
	s_add_i32 m0, s26, 0x2000
	s_nop 0
	global_load_lds_dwordx4 v[140:141], off
	v_lshl_add_u64 v[140:141], v[188:189], 0, s[82:83]
	s_mov_b32 m0, s51
	s_nop 0
	global_load_lds_dwordx4 v[140:141], off
	v_lshl_add_u64 v[140:141], v[196:197], 0, s[82:83]
	s_mov_b32 m0, s52
	s_nop 0
	global_load_lds_dwordx4 v[140:141], off
	s_waitcnt vmcnt(8)
	s_waitcnt lgkmcnt(0)
	s_barrier
	v_mfma_f32_16x16x32_bf16 v[60:63], v[148:151], v[202:205], v[60:63]
	v_mfma_f32_16x16x32_bf16 v[56:59], v[164:167], v[202:205], v[56:59]
	v_mfma_f32_16x16x32_bf16 v[44:47], v[148:151], v[210:213], v[44:47]
	v_mfma_f32_16x16x32_bf16 v[40:43], v[164:167], v[210:213], v[40:43]
	v_mfma_f32_16x16x32_bf16 v[28:31], v[148:151], v[218:221], v[28:31]
	v_mfma_f32_16x16x32_bf16 v[24:27], v[164:167], v[218:221], v[24:27]
	v_mfma_f32_16x16x32_bf16 v[12:15], v[148:151], v[226:229], v[12:15]
	v_mfma_f32_16x16x32_bf16 v[8:11], v[164:167], v[226:229], v[8:11]
	v_mfma_f32_16x16x32_bf16 v[60:63], v[160:163], v[206:209], v[60:63]
	v_mfma_f32_16x16x32_bf16 v[56:59], v[168:171], v[206:209], v[56:59]
	v_mfma_f32_16x16x32_bf16 v[44:47], v[160:163], v[214:217], v[44:47]
	v_mfma_f32_16x16x32_bf16 v[40:43], v[168:171], v[214:217], v[40:43]
	v_mfma_f32_16x16x32_bf16 v[28:31], v[160:163], v[222:225], v[28:31]
	v_mfma_f32_16x16x32_bf16 v[24:27], v[168:171], v[222:225], v[24:27]
	v_mfma_f32_16x16x32_bf16 v[12:15], v[160:163], v[230:233], v[12:15]
	v_mfma_f32_16x16x32_bf16 v[8:11], v[168:171], v[230:233], v[8:11]
	v_mfma_f32_16x16x32_bf16 v[52:55], v[172:175], v[202:205], v[52:55]
	v_mfma_f32_16x16x32_bf16 v[48:51], v[180:183], v[202:205], v[48:51]
	v_mfma_f32_16x16x32_bf16 v[36:39], v[172:175], v[210:213], v[36:39]
	v_mfma_f32_16x16x32_bf16 v[32:35], v[180:183], v[210:213], v[32:35]
	v_mfma_f32_16x16x32_bf16 v[20:23], v[172:175], v[218:221], v[20:23]
	v_mfma_f32_16x16x32_bf16 v[16:19], v[180:183], v[218:221], v[16:19]
	v_mfma_f32_16x16x32_bf16 v[4:7], v[172:175], v[226:229], v[4:7]
	v_mfma_f32_16x16x32_bf16 v[0:3], v[180:183], v[226:229], v[0:3]
	v_mfma_f32_16x16x32_bf16 v[52:55], v[176:179], v[206:209], v[52:55]
	v_mfma_f32_16x16x32_bf16 v[48:51], v[184:187], v[206:209], v[48:51]
	v_mfma_f32_16x16x32_bf16 v[36:39], v[176:179], v[214:217], v[36:39]
	v_mfma_f32_16x16x32_bf16 v[32:35], v[184:187], v[214:217], v[32:35]
	v_mfma_f32_16x16x32_bf16 v[20:23], v[176:179], v[222:225], v[20:23]
	v_mfma_f32_16x16x32_bf16 v[16:19], v[184:187], v[222:225], v[16:19]
	v_mfma_f32_16x16x32_bf16 v[4:7], v[176:179], v[230:233], v[4:7]
	v_mfma_f32_16x16x32_bf16 v[0:3], v[184:187], v[230:233], v[0:3]
	s_barrier
	s_add_i32 s64, s64, 2
	s_add_u32 s22, s22, 0x100
	s_addc_u32 s23, s23, 0
	s_add_u32 s62, s62, 0x100
	s_addc_u32 s63, s63, 0
	s_cmp_gt_u32 s64, 13
	s_cbranch_scc1 .LBB0_183

; #define PG8_STAGE(bufoff, gbase, voff) do { _Pragma("unroll") for (int _i = 0; _i < 2; ++_i) \
;         __builtin_amdgcn_global_load_lds((const unsigned*)((const char*)(gbase) + (voff)[_i]), (PG8_LAS unsigned*)(lds + (bufoff) + ldsw + _i * 8192), 16, 0, 0); } while (0)
; #define PG8_LDA(dst, b, h) do { _Pragma("unroll") for (int m = 0; m < 4; ++m) _Pragma("unroll") for (int k = 0; k < 2; ++k) dst[m][k] = *(const PG8_LAS bf16x8*)(lds + PG8_SA(b, h) + aoff + m * 2048 + k * 1024); } while (0)
; #define PG8_LDB(dst, b, h) do { _Pragma("unroll") for (int n = 0; n < 2; ++n) _Pragma("unroll") for (int k = 0; k < 2; ++k) dst[n][k] = *(const PG8_LAS bf16x8*)(lds + PG8_SB(b, h) + boff + n * 2048 + k * 1024); } while (0)
; #define PG8_MMA(ai, bj, At, Bt) do { __builtin_amdgcn_s_setprio(1); _Pragma("unroll") for (int m = 0; m < 4; ++m) _Pragma("unroll") for (int n = 0; n < 2; ++n) _Pragma("unroll") for (int k = 0; k < 2; ++k) \
;         acc[ai][bj][m][n] = __builtin_amdgcn_mfma_f32_16x16x32_bf16(Bt[n][k], At[m][k], acc[ai][bj][m][n], 0, 0, 0); __builtin_amdgcn_s_setprio(0); } while (0)
; #define PG8_WAIT_V(n) asm volatile("s_waitcnt vmcnt(" #n ")" ::: "memory")
; #define PG8_BAR __builtin_amdgcn_s_barrier()
; template <class Epi, class Sched, bool ALIGN_EPI = false, bool SP2 = false, bool HALFM = false>
; __device__ __forceinline__ void gemm_phase(PG8_LAS unsigned char* lds, const Gemm g, const Sched& S, const Epi& E) {
;     ...
;             const bool last = (t == nt - 2);
;             const char* a1 = cA + (size_t)(t + 1) * kstep;
;             const char* a2 = last ? nA : cA + (size_t)(t + 2) * kstep; const char* b2 = last ? nB : cB + (size_t)(t + 2) * kstep;
;             const char* a3 = a2 + kstep; const char* b3 = b2 + kstep;
;             if (last && has_next) S.a_ready(nxt);
;             if constexpr (SP2) {
;             PG8_LDB(B0, 0, 0); PG8_LDB(B1, 0, 1); PG8_SCHED; PG8_LDA(At, 0, 0); PG8_STAGE(PG8_SA(1, 1), a1 + hstep, voffA);
;             PG8_WAIT_V(8); PG8_WAIT_L(0); PG8_BAR; PG8_MMA(0, 0, At, B0); PG8_MMA(0, 1, At, B1); PG8_BAR; PG8_SCHED;
;             if constexpr (!HALFM) PG8_LDA(At, 0, 1); PG8_STAGE(PG8_SB(0, 0), b2, voffB); PG8_STAGE(PG8_SB(0, 1), b2 + hstep, voffB); PG8_STAGE(PG8_SA(0, 0), a2, voffA);
;             PG8_WAIT_V(8); PG8_WAIT_L(0); PG8_BAR; if constexpr (!HALFM) { PG8_MMA(1, 0, At, B0); PG8_MMA(1, 1, At, B1); } PG8_BAR; PG8_SCHED;
.LBB0_274:
	s_add_u32 s22, s20, 0x100
	s_addc_u32 s23, s21, 0
	s_add_i32 s61, 0, 0x10000
	s_cmp_eq_u32 s60, 40
	s_cselect_b32 s27, s17, s23
	s_cselect_b32 s26, s16, s22
	s_cselect_b32 s25, s19, s59
	s_cselect_b32 s24, s18, s58
	s_add_i32 s62, 0, 0x14000
	v_add_u32_e32 v142, s61, v203
	v_add_u32_e32 v174, s62, v203
	ds_read_b128 v[130:133], v142
	ds_read_b128 v[134:137], v142 offset:1024
	ds_read_b128 v[138:141], v142 offset:2048
	ds_read_b128 v[142:145], v142 offset:3072
	ds_read_b128 v[146:149], v174
	ds_read_b128 v[150:153], v174 offset:1024
	ds_read_b128 v[170:173], v174 offset:2048
	ds_read_b128 v[174:177], v174 offset:3072
	v_lshl_add_u64 v[196:197], s[20:21], 0, v[166:167]
	s_add_i32 m0, s46, 0xc000
	ds_read_b128 v[178:181], v205
	ds_read_b128 v[182:185], v205 offset:1024
	ds_read_b128 v[186:189], v205 offset:2048
	ds_read_b128 v[206:209], v205 offset:3072
	ds_read_b128 v[210:213], v205 offset:4096
	ds_read_b128 v[214:217], v205 offset:5120
	ds_read_b128 v[218:221], v205 offset:6144
	ds_read_b128 v[222:225], v205 offset:7168
	global_load_lds_dwordx4 v[196:197], off
	v_lshl_add_u64 v[196:197], s[20:21], 0, v[168:169]
	s_add_i32 m0, s46, 0xe000
	s_nop 0
	global_load_lds_dwordx4 v[196:197], off
	s_waitcnt vmcnt(8)
	s_waitcnt lgkmcnt(0)
	s_barrier
	v_mfma_f32_16x16x32_bf16 v[126:129], v[130:133], v[178:181], v[126:129]
	v_mfma_f32_16x16x32_bf16 v[122:125], v[138:141], v[178:181], v[122:125]
	v_mfma_f32_16x16x32_bf16 v[110:113], v[130:133], v[186:189], v[110:113]
	v_mfma_f32_16x16x32_bf16 v[106:109], v[138:141], v[186:189], v[106:109]
	v_mfma_f32_16x16x32_bf16 v[94:97], v[130:133], v[210:213], v[94:97]
	v_mfma_f32_16x16x32_bf16 v[90:93], v[138:141], v[210:213], v[90:93]
	v_mfma_f32_16x16x32_bf16 v[76:79], v[130:133], v[218:221], v[76:79]
	v_mfma_f32_16x16x32_bf16 v[72:75], v[138:141], v[218:221], v[72:75]
	v_mfma_f32_16x16x32_bf16 v[126:129], v[134:137], v[182:185], v[126:129]
	v_mfma_f32_16x16x32_bf16 v[122:125], v[142:145], v[182:185], v[122:125]
	v_mfma_f32_16x16x32_bf16 v[110:113], v[134:137], v[206:209], v[110:113]
	v_mfma_f32_16x16x32_bf16 v[106:109], v[142:145], v[206:209], v[106:109]
	v_mfma_f32_16x16x32_bf16 v[94:97], v[134:137], v[214:217], v[94:97]
	v_mfma_f32_16x16x32_bf16 v[90:93], v[142:145], v[214:217], v[90:93]
	v_mfma_f32_16x16x32_bf16 v[76:79], v[134:137], v[222:225], v[76:79]
	v_mfma_f32_16x16x32_bf16 v[72:75], v[142:145], v[222:225], v[72:75]
	v_mfma_f32_16x16x32_bf16 v[118:121], v[146:149], v[178:181], v[118:121]
	v_mfma_f32_16x16x32_bf16 v[114:117], v[170:173], v[178:181], v[114:117]
	v_mfma_f32_16x16x32_bf16 v[102:105], v[146:149], v[186:189], v[102:105]
	v_mfma_f32_16x16x32_bf16 v[98:101], v[170:173], v[186:189], v[98:101]
	v_mfma_f32_16x16x32_bf16 v[86:89], v[146:149], v[210:213], v[86:89]
	v_mfma_f32_16x16x32_bf16 v[82:85], v[170:173], v[210:213], v[82:85]
	v_mfma_f32_16x16x32_bf16 v[68:71], v[146:149], v[218:221], v[68:71]
	v_mfma_f32_16x16x32_bf16 v[64:67], v[170:173], v[218:221], v[64:67]
	v_mfma_f32_16x16x32_bf16 v[118:121], v[150:153], v[182:185], v[118:121]
	v_mfma_f32_16x16x32_bf16 v[114:117], v[174:177], v[182:185], v[114:117]
	v_mfma_f32_16x16x32_bf16 v[102:105], v[150:153], v[206:209], v[102:105]
	v_mfma_f32_16x16x32_bf16 v[98:101], v[174:177], v[206:209], v[98:101]
	v_mfma_f32_16x16x32_bf16 v[86:89], v[150:153], v[214:217], v[86:89]
	v_mfma_f32_16x16x32_bf16 v[82:85], v[174:177], v[214:217], v[82:85]
	v_mfma_f32_16x16x32_bf16 v[68:71], v[150:153], v[222:225], v[68:71]
	v_mfma_f32_16x16x32_bf16 v[64:67], v[174:177], v[222:225], v[64:67]
	s_barrier
	s_add_i32 s20, s61, s28
	v_lshl_add_u64 v[196:197], s[24:25], 0, v[80:81]
	s_mov_b32 m0, s20
	ds_read_b128 v[178:181], v205 offset:16384
	ds_read_b128 v[182:185], v205 offset:17408
	ds_read_b128 v[186:189], v205 offset:18432
	ds_read_b128 v[206:209], v205 offset:19456
	ds_read_b128 v[210:213], v205 offset:20480
	ds_read_b128 v[214:217], v205 offset:21504
	ds_read_b128 v[218:221], v205 offset:22528
	ds_read_b128 v[222:225], v205 offset:23552
	global_load_lds_dwordx4 v[196:197], off
	s_add_i32 m0, s20, 0x2000
	s_add_u32 s20, s24, 0xb0000
	v_lshl_add_u64 v[198:199], s[24:25], 0, v[160:161]
	s_addc_u32 s21, s25, 0
	s_add_i32 s61, s62, s28
	global_load_lds_dwordx4 v[198:199], off
	v_lshl_add_u64 v[226:227], s[20:21], 0, v[80:81]
	s_mov_b32 m0, s61
	v_lshl_add_u64 v[228:229], s[26:27], 0, v[162:163]
	global_load_lds_dwordx4 v[226:227], off
	v_lshl_add_u64 v[226:227], s[20:21], 0, v[160:161]
	s_add_i32 m0, s61, 0x2000
	s_nop 0
	global_load_lds_dwordx4 v[226:227], off
	v_lshl_add_u64 v[226:227], s[26:27], 0, v[164:165]
	s_mov_b32 m0, s46
	s_nop 0
	global_load_lds_dwordx4 v[226:227], off
	s_mov_b32 m0, s47
	s_nop 0
	global_load_lds_dwordx4 v[228:229], off
	s_waitcnt vmcnt(8)
	s_waitcnt lgkmcnt(0)
	s_barrier
; #define PG8_STAGE(bufoff, gbase, voff) do { _Pragma("unroll") for (int _i = 0; _i < 2; ++_i) \
;         __builtin_amdgcn_global_load_lds((const unsigned*)((const char*)(gbase) + (voff)[_i]), (PG8_LAS unsigned*)(lds + (bufoff) + ldsw + _i * 8192), 16, 0, 0); } while (0)
; #define PG8_LDA(dst, b, h) do { _Pragma("unroll") for (int m = 0; m < 4; ++m) _Pragma("unroll") for (int k = 0; k < 2; ++k) dst[m][k] = *(const PG8_LAS bf16x8*)(lds + PG8_SA(b, h) + aoff + m * 2048 + k * 1024); } while (0)
; #define PG8_LDB(dst, b, h) do { _Pragma("unroll") for (int n = 0; n < 2; ++n) _Pragma("unroll") for (int k = 0; k < 2; ++k) dst[n][k] = *(const PG8_LAS bf16x8*)(lds + PG8_SB(b, h) + boff + n * 2048 + k * 1024); } while (0)
; #define PG8_MMA(ai, bj, At, Bt) do { __builtin_amdgcn_s_setprio(1); _Pragma("unroll") for (int m = 0; m < 4; ++m) _Pragma("unroll") for (int n = 0; n < 2; ++n) _Pragma("unroll") for (int k = 0; k < 2; ++k) \
;         acc[ai][bj][m][n] = __builtin_amdgcn_mfma_f32_16x16x32_bf16(Bt[n][k], At[m][k], acc[ai][bj][m][n], 0, 0, 0); __builtin_amdgcn_s_setprio(0); } while (0)
; #define PG8_WAIT_V(n) asm volatile("s_waitcnt vmcnt(" #n ")" ::: "memory")
; #define PG8_WAIT_L(n) asm volatile("s_waitcnt lgkmcnt(" #n ")" ::: "memory")
; #define PG8_BAR __builtin_amdgcn_s_barrier()
; #define PG8_SCHED __builtin_amdgcn_sched_barrier(0)
; template <class Epi, class Sched, bool ALIGN_EPI = false, bool SP2 = false, bool HALFM = false>
; __device__ __forceinline__ void gemm_phase(PG8_LAS unsigned char* lds, const Gemm g, const Sched& S, const Epi& E) {
;     ...
;             PG8_WAIT_V(8); PG8_WAIT_L(0); PG8_BAR; if constexpr (!HALFM) { PG8_MMA(1, 0, At, B0); PG8_MMA(1, 1, At, B1); } PG8_BAR; PG8_SCHED;
;             PG8_LDB(B0, 1, 0); PG8_LDB(B1, 1, 1); PG8_SCHED; PG8_LDA(At, 1, 0); PG8_STAGE(PG8_SA(0, 1), a2 + hstep, voffA);
;             PG8_WAIT_V(8); PG8_WAIT_L(0); PG8_BAR; PG8_MMA(0, 0, At, B0); PG8_MMA(0, 1, At, B1); PG8_BAR; PG8_SCHED;
	v_mfma_f32_16x16x32_bf16 v[60:63], v[130:133], v[178:181], v[60:63]
	v_mfma_f32_16x16x32_bf16 v[56:59], v[138:141], v[178:181], v[56:59]
	v_mfma_f32_16x16x32_bf16 v[44:47], v[130:133], v[186:189], v[44:47]
	v_mfma_f32_16x16x32_bf16 v[40:43], v[138:141], v[186:189], v[40:43]
	v_mfma_f32_16x16x32_bf16 v[28:31], v[130:133], v[210:213], v[28:31]
	v_mfma_f32_16x16x32_bf16 v[24:27], v[138:141], v[210:213], v[24:27]
	v_mfma_f32_16x16x32_bf16 v[12:15], v[130:133], v[218:221], v[12:15]
	v_mfma_f32_16x16x32_bf16 v[8:11], v[138:141], v[218:221], v[8:11]
	v_mfma_f32_16x16x32_bf16 v[60:63], v[134:137], v[182:185], v[60:63]
	v_mfma_f32_16x16x32_bf16 v[56:59], v[142:145], v[182:185], v[56:59]
	v_mfma_f32_16x16x32_bf16 v[44:47], v[134:137], v[206:209], v[44:47]
	v_mfma_f32_16x16x32_bf16 v[40:43], v[142:145], v[206:209], v[40:43]
	v_mfma_f32_16x16x32_bf16 v[28:31], v[134:137], v[214:217], v[28:31]
	v_mfma_f32_16x16x32_bf16 v[24:27], v[142:145], v[214:217], v[24:27]
	v_mfma_f32_16x16x32_bf16 v[12:15], v[134:137], v[222:225], v[12:15]
	v_mfma_f32_16x16x32_bf16 v[8:11], v[142:145], v[222:225], v[8:11]
	v_mfma_f32_16x16x32_bf16 v[52:55], v[146:149], v[178:181], v[52:55]
	v_mfma_f32_16x16x32_bf16 v[48:51], v[170:173], v[178:181], v[48:51]
	v_mfma_f32_16x16x32_bf16 v[36:39], v[146:149], v[186:189], v[36:39]
	v_mfma_f32_16x16x32_bf16 v[32:35], v[170:173], v[186:189], v[32:35]
	v_mfma_f32_16x16x32_bf16 v[20:23], v[146:149], v[210:213], v[20:23]
	v_mfma_f32_16x16x32_bf16 v[16:19], v[170:173], v[210:213], v[16:19]
	v_mfma_f32_16x16x32_bf16 v[4:7], v[146:149], v[218:221], v[4:7]
	v_mfma_f32_16x16x32_bf16 v[0:3], v[170:173], v[218:221], v[0:3]
	v_mfma_f32_16x16x32_bf16 v[52:55], v[150:153], v[182:185], v[52:55]
	v_mfma_f32_16x16x32_bf16 v[48:51], v[174:177], v[182:185], v[48:51]
	v_mfma_f32_16x16x32_bf16 v[36:39], v[150:153], v[206:209], v[36:39]
	v_mfma_f32_16x16x32_bf16 v[32:35], v[174:177], v[206:209], v[32:35]
	v_mfma_f32_16x16x32_bf16 v[20:23], v[150:153], v[214:217], v[20:23]
	v_mfma_f32_16x16x32_bf16 v[16:19], v[174:177], v[214:217], v[16:19]
	v_mfma_f32_16x16x32_bf16 v[4:7], v[150:153], v[222:225], v[4:7]
	v_mfma_f32_16x16x32_bf16 v[0:3], v[174:177], v[222:225], v[0:3]
	s_barrier
	s_add_i32 s61, 0, 0x18000
	s_add_i32 s62, 0, 0x1c000
	v_add_u32_e32 v142, s61, v203
	v_add_u32_e32 v174, s62, v203
	ds_read_b128 v[130:133], v142
	ds_read_b128 v[134:137], v142 offset:1024
	ds_read_b128 v[138:141], v142 offset:2048
	ds_read_b128 v[142:145], v142 offset:3072
	ds_read_b128 v[146:149], v174
	ds_read_b128 v[150:153], v174 offset:1024
	ds_read_b128 v[170:173], v174 offset:2048
	ds_read_b128 v[174:177], v174 offset:3072
	s_add_u32 s20, s26, 0xb0000
	s_addc_u32 s21, s27, 0
	s_mov_b32 m0, s48
	v_lshl_add_u64 v[230:231], s[20:21], 0, v[164:165]
	ds_read_b128 v[178:181], v205 offset:32768
	ds_read_b128 v[182:185], v205 offset:33792
	ds_read_b128 v[186:189], v205 offset:34816
	ds_read_b128 v[206:209], v205 offset:35840
	ds_read_b128 v[210:213], v205 offset:36864
	ds_read_b128 v[214:217], v205 offset:37888
	ds_read_b128 v[218:221], v205 offset:38912
	ds_read_b128 v[222:225], v205 offset:39936
	global_load_lds_dwordx4 v[230:231], off
	v_lshl_add_u64 v[230:231], s[20:21], 0, v[162:163]
	s_mov_b32 m0, s49
	s_nop 0
	global_load_lds_dwordx4 v[230:231], off
	s_waitcnt vmcnt(8)
	s_waitcnt lgkmcnt(0)
	s_barrier
	v_mfma_f32_16x16x32_bf16 v[126:129], v[130:133], v[178:181], v[126:129]
	v_mfma_f32_16x16x32_bf16 v[122:125], v[138:141], v[178:181], v[122:125]
	v_mfma_f32_16x16x32_bf16 v[110:113], v[130:133], v[186:189], v[110:113]
	v_mfma_f32_16x16x32_bf16 v[106:109], v[138:141], v[186:189], v[106:109]
	v_mfma_f32_16x16x32_bf16 v[94:97], v[130:133], v[210:213], v[94:97]
	v_mfma_f32_16x16x32_bf16 v[90:93], v[138:141], v[210:213], v[90:93]
	v_mfma_f32_16x16x32_bf16 v[76:79], v[130:133], v[218:221], v[76:79]
	v_mfma_f32_16x16x32_bf16 v[72:75], v[138:141], v[218:221], v[72:75]
	v_mfma_f32_16x16x32_bf16 v[126:129], v[134:137], v[182:185], v[126:129]
	v_mfma_f32_16x16x32_bf16 v[122:125], v[142:145], v[182:185], v[122:125]
	v_mfma_f32_16x16x32_bf16 v[110:113], v[134:137], v[206:209], v[110:113]
	v_mfma_f32_16x16x32_bf16 v[106:109], v[142:145], v[206:209], v[106:109]
	v_mfma_f32_16x16x32_bf16 v[94:97], v[134:137], v[214:217], v[94:97]
	v_mfma_f32_16x16x32_bf16 v[90:93], v[142:145], v[214:217], v[90:93]
	v_mfma_f32_16x16x32_bf16 v[76:79], v[134:137], v[222:225], v[76:79]
	v_mfma_f32_16x16x32_bf16 v[72:75], v[142:145], v[222:225], v[72:75]
	v_mfma_f32_16x16x32_bf16 v[118:121], v[146:149], v[178:181], v[118:121]
	v_mfma_f32_16x16x32_bf16 v[114:117], v[170:173], v[178:181], v[114:117]
	v_mfma_f32_16x16x32_bf16 v[102:105], v[146:149], v[186:189], v[102:105]
	v_mfma_f32_16x16x32_bf16 v[98:101], v[170:173], v[186:189], v[98:101]
	v_mfma_f32_16x16x32_bf16 v[86:89], v[146:149], v[210:213], v[86:89]
	v_mfma_f32_16x16x32_bf16 v[82:85], v[170:173], v[210:213], v[82:85]
	v_mfma_f32_16x16x32_bf16 v[68:71], v[146:149], v[218:221], v[68:71]
	v_mfma_f32_16x16x32_bf16 v[64:67], v[170:173], v[218:221], v[64:67]
	v_mfma_f32_16x16x32_bf16 v[118:121], v[150:153], v[182:185], v[118:121]
	v_mfma_f32_16x16x32_bf16 v[114:117], v[174:177], v[182:185], v[114:117]
	v_mfma_f32_16x16x32_bf16 v[102:105], v[150:153], v[206:209], v[102:105]
	v_mfma_f32_16x16x32_bf16 v[98:101], v[174:177], v[206:209], v[98:101]
	v_mfma_f32_16x16x32_bf16 v[86:89], v[150:153], v[214:217], v[86:89]
	v_mfma_f32_16x16x32_bf16 v[82:85], v[174:177], v[214:217], v[82:85]
	v_mfma_f32_16x16x32_bf16 v[68:71], v[150:153], v[222:225], v[68:71]
	v_mfma_f32_16x16x32_bf16 v[64:67], v[174:177], v[222:225], v[64:67]
	s_barrier
; #define PG8_STAGE(bufoff, gbase, voff) do { _Pragma("unroll") for (int _i = 0; _i < 2; ++_i) \
;         __builtin_amdgcn_global_load_lds((const unsigned*)((const char*)(gbase) + (voff)[_i]), (PG8_LAS unsigned*)(lds + (bufoff) + ldsw + _i * 8192), 16, 0, 0); } while (0)
; #define PG8_LDA(dst, b, h) do { _Pragma("unroll") for (int m = 0; m < 4; ++m) _Pragma("unroll") for (int k = 0; k < 2; ++k) dst[m][k] = *(const PG8_LAS bf16x8*)(lds + PG8_SA(b, h) + aoff + m * 2048 + k * 1024); } while (0)
; #define PG8_MMA(ai, bj, At, Bt) do { __builtin_amdgcn_s_setprio(1); _Pragma("unroll") for (int m = 0; m < 4; ++m) _Pragma("unroll") for (int n = 0; n < 2; ++n) _Pragma("unroll") for (int k = 0; k < 2; ++k) \
;         acc[ai][bj][m][n] = __builtin_amdgcn_mfma_f32_16x16x32_bf16(Bt[n][k], At[m][k], acc[ai][bj][m][n], 0, 0, 0); __builtin_amdgcn_s_setprio(0); } while (0)
; #define PG8_WAIT_V(n) asm volatile("s_waitcnt vmcnt(" #n ")" ::: "memory")
; #define PG8_WAIT_L(n) asm volatile("s_waitcnt lgkmcnt(" #n ")" ::: "memory")
; #define PG8_BAR __builtin_amdgcn_s_barrier()
; #define PG8_SCHED __builtin_amdgcn_sched_barrier(0)
; template <class Epi, class Sched, bool ALIGN_EPI = false, bool SP2 = false, bool HALFM = false>
; __device__ __forceinline__ void gemm_phase(PG8_LAS unsigned char* lds, const Gemm g, const Sched& S, const Epi& E) {
;     ...
;             if constexpr (!HALFM) PG8_LDA(At, 1, 1); PG8_STAGE(PG8_SB(1, 0), b3, voffB); PG8_STAGE(PG8_SB(1, 1), b3 + hstep, voffB); PG8_STAGE(PG8_SA(1, 0), a3, voffA);
;             PG8_WAIT_V(8); PG8_WAIT_L(0); PG8_BAR; if constexpr (!HALFM) { PG8_MMA(1, 0, At, B0); PG8_MMA(1, 1, At, B1); } PG8_BAR; PG8_SCHED;
;     ...
;         if (!has_next) break;
	s_add_i32 s20, s61, s28
	v_lshl_add_u64 v[196:197], v[196:197], 0, s[82:83]
	s_mov_b32 m0, s20
	ds_read_b128 v[178:181], v205 offset:49152
	ds_read_b128 v[182:185], v205 offset:50176
	ds_read_b128 v[186:189], v205 offset:51200
	ds_read_b128 v[206:209], v205 offset:52224
	ds_read_b128 v[210:213], v205 offset:53248
	ds_read_b128 v[214:217], v205 offset:54272
	ds_read_b128 v[218:221], v205 offset:55296
	ds_read_b128 v[222:225], v205 offset:56320
	global_load_lds_dwordx4 v[196:197], off
	s_add_i32 m0, s20, 0x2000
	s_add_u32 s20, s24, 0xb0080
	v_lshl_add_u64 v[196:197], v[198:199], 0, s[82:83]
	s_addc_u32 s21, s25, 0
	s_add_i32 s24, s62, s28
	global_load_lds_dwordx4 v[196:197], off
	v_lshl_add_u64 v[196:197], s[20:21], 0, v[80:81]
	s_mov_b32 m0, s24
	s_nop 0
	global_load_lds_dwordx4 v[196:197], off
	v_lshl_add_u64 v[196:197], s[20:21], 0, v[160:161]
	s_add_i32 m0, s24, 0x2000
	s_nop 0
	global_load_lds_dwordx4 v[196:197], off
	v_lshl_add_u64 v[196:197], v[226:227], 0, s[82:83]
	s_mov_b32 m0, s52
	s_nop 0
	global_load_lds_dwordx4 v[196:197], off
	v_lshl_add_u64 v[196:197], v[228:229], 0, s[82:83]
	s_mov_b32 m0, s53
	s_nop 0
	global_load_lds_dwordx4 v[196:197], off
	s_waitcnt vmcnt(8)
	s_waitcnt lgkmcnt(0)
	s_barrier
	v_mfma_f32_16x16x32_bf16 v[60:63], v[130:133], v[178:181], v[60:63]
	v_mfma_f32_16x16x32_bf16 v[56:59], v[138:141], v[178:181], v[56:59]
	v_mfma_f32_16x16x32_bf16 v[44:47], v[130:133], v[186:189], v[44:47]
	v_mfma_f32_16x16x32_bf16 v[40:43], v[138:141], v[186:189], v[40:43]
	v_mfma_f32_16x16x32_bf16 v[28:31], v[130:133], v[210:213], v[28:31]
	v_mfma_f32_16x16x32_bf16 v[24:27], v[138:141], v[210:213], v[24:27]
	v_mfma_f32_16x16x32_bf16 v[12:15], v[130:133], v[218:221], v[12:15]
	v_mfma_f32_16x16x32_bf16 v[8:11], v[138:141], v[218:221], v[8:11]
	v_mfma_f32_16x16x32_bf16 v[60:63], v[134:137], v[182:185], v[60:63]
	v_mfma_f32_16x16x32_bf16 v[56:59], v[142:145], v[182:185], v[56:59]
	v_mfma_f32_16x16x32_bf16 v[44:47], v[134:137], v[206:209], v[44:47]
	v_mfma_f32_16x16x32_bf16 v[40:43], v[142:145], v[206:209], v[40:43]
	v_mfma_f32_16x16x32_bf16 v[28:31], v[134:137], v[214:217], v[28:31]
	v_mfma_f32_16x16x32_bf16 v[24:27], v[142:145], v[214:217], v[24:27]
	v_mfma_f32_16x16x32_bf16 v[12:15], v[134:137], v[222:225], v[12:15]
	v_mfma_f32_16x16x32_bf16 v[8:11], v[142:145], v[222:225], v[8:11]
	v_mfma_f32_16x16x32_bf16 v[52:55], v[146:149], v[178:181], v[52:55]
	v_mfma_f32_16x16x32_bf16 v[48:51], v[170:173], v[178:181], v[48:51]
	v_mfma_f32_16x16x32_bf16 v[36:39], v[146:149], v[186:189], v[36:39]
	v_mfma_f32_16x16x32_bf16 v[32:35], v[170:173], v[186:189], v[32:35]
	v_mfma_f32_16x16x32_bf16 v[20:23], v[146:149], v[210:213], v[20:23]
	v_mfma_f32_16x16x32_bf16 v[16:19], v[170:173], v[210:213], v[16:19]
	v_mfma_f32_16x16x32_bf16 v[4:7], v[146:149], v[218:221], v[4:7]
	v_mfma_f32_16x16x32_bf16 v[0:3], v[170:173], v[218:221], v[0:3]
	v_mfma_f32_16x16x32_bf16 v[52:55], v[150:153], v[182:185], v[52:55]
	v_mfma_f32_16x16x32_bf16 v[48:51], v[174:177], v[182:185], v[48:51]
	v_mfma_f32_16x16x32_bf16 v[36:39], v[150:153], v[206:209], v[36:39]
	v_mfma_f32_16x16x32_bf16 v[32:35], v[174:177], v[206:209], v[32:35]
	v_mfma_f32_16x16x32_bf16 v[20:23], v[150:153], v[214:217], v[20:23]
	v_mfma_f32_16x16x32_bf16 v[16:19], v[174:177], v[214:217], v[16:19]
	v_mfma_f32_16x16x32_bf16 v[4:7], v[150:153], v[222:225], v[4:7]
	v_mfma_f32_16x16x32_bf16 v[0:3], v[174:177], v[222:225], v[0:3]
	s_barrier
	s_add_i32 s60, s60, 2
	s_add_u32 s58, s58, 0x100
	s_addc_u32 s59, s59, 0
	s_cmp_gt_u32 s60, 41
	s_mov_b64 s[20:21], s[22:23]
	s_cbranch_scc0 .LBB0_274
	s_and_b64 vcc, exec, s[12:13]
	s_cbranch_vccz .LBB0_277
	s_barrier

; #define PG8_STAGE(bufoff, gbase, voff) do { _Pragma("unroll") for (int _i = 0; _i < 2; ++_i) \
;         __builtin_amdgcn_global_load_lds((const unsigned*)((const char*)(gbase) + (voff)[_i]), (PG8_LAS unsigned*)(lds + (bufoff) + ldsw + _i * 8192), 16, 0, 0); } while (0)
; #define PG8_LDA(dst, b, h) do { _Pragma("unroll") for (int m = 0; m < 4; ++m) _Pragma("unroll") for (int k = 0; k < 2; ++k) dst[m][k] = *(const PG8_LAS bf16x8*)(lds + PG8_SA(b, h) + aoff + m * 2048 + k * 1024); } while (0)
; #define PG8_LDB(dst, b, h) do { _Pragma("unroll") for (int n = 0; n < 2; ++n) _Pragma("unroll") for (int k = 0; k < 2; ++k) dst[n][k] = *(const PG8_LAS bf16x8*)(lds + PG8_SB(b, h) + boff + n * 2048 + k * 1024); } while (0)
; #define PG8_MMA(ai, bj, At, Bt) do { __builtin_amdgcn_s_setprio(1); _Pragma("unroll") for (int m = 0; m < 4; ++m) _Pragma("unroll") for (int n = 0; n < 2; ++n) _Pragma("unroll") for (int k = 0; k < 2; ++k) \
;         acc[ai][bj][m][n] = __builtin_amdgcn_mfma_f32_16x16x32_bf16(Bt[n][k], At[m][k], acc[ai][bj][m][n], 0, 0, 0); __builtin_amdgcn_s_setprio(0); } while (0)
; #define PG8_WAIT_V(n) asm volatile("s_waitcnt vmcnt(" #n ")" ::: "memory")
; #define PG8_BAR __builtin_amdgcn_s_barrier()
; template <class Epi, class Sched, bool ALIGN_EPI = false, bool SP2 = false, bool HALFM = false>
; __device__ __forceinline__ void gemm_phase(PG8_LAS unsigned char* lds, const Gemm g, const Sched& S, const Epi& E) {
;     ...
;             const bool last = (t == nt - 2);
;             const char* a1 = cA + (size_t)(t + 1) * kstep;
;             const char* a2 = last ? nA : cA + (size_t)(t + 2) * kstep; const char* b2 = last ? nB : cB + (size_t)(t + 2) * kstep;
;             const char* a3 = a2 + kstep; const char* b3 = b2 + kstep;
;             if (last && has_next) S.a_ready(nxt);
;             if constexpr (SP2) {
;             PG8_LDB(B0, 0, 0); PG8_LDB(B1, 0, 1); PG8_SCHED; PG8_LDA(At, 0, 0); PG8_STAGE(PG8_SA(1, 1), a1 + hstep, voffA);
;             PG8_WAIT_V(8); PG8_WAIT_L(0); PG8_BAR; PG8_MMA(0, 0, At, B0); PG8_MMA(0, 1, At, B1); PG8_BAR; PG8_SCHED;
;             if constexpr (!HALFM) PG8_LDA(At, 0, 1); PG8_STAGE(PG8_SB(0, 0), b2, voffB); PG8_STAGE(PG8_SB(0, 1), b2 + hstep, voffB); PG8_STAGE(PG8_SA(0, 0), a2, voffA);
;             PG8_WAIT_V(8); PG8_WAIT_L(0); PG8_BAR; if constexpr (!HALFM) { PG8_MMA(1, 0, At, B0); PG8_MMA(1, 1, At, B1); } PG8_BAR; PG8_SCHED;
.LBB0_413:
	s_add_u32 s28, s24, 0xfffc0080
	s_addc_u32 s29, s25, -1
	s_and_b64 s[26:27], s[26:27], exec
	s_cselect_b32 s29, s29, s15
	s_cselect_b32 s28, s28, s60
	s_cselect_b32 s27, s65, s13
	s_cselect_b32 s26, s64, s61
	s_add_i32 s67, 0, 0x10000
	s_add_i32 s70, 0, 0x14000
	v_add_u32_e32 v142, s67, v179
	v_add_u32_e32 v183, s70, v179
	ds_read_b128 v[130:133], v142
	ds_read_b128 v[134:137], v142 offset:1024
	ds_read_b128 v[138:141], v142 offset:2048
	ds_read_b128 v[142:145], v142 offset:3072
	ds_read_b128 v[166:169], v183
	ds_read_b128 v[170:173], v183 offset:1024
	ds_read_b128 v[174:177], v183 offset:2048
	ds_read_b128 v[184:187], v183 offset:3072
	v_lshl_add_u64 v[188:189], s[24:25], 0, v[162:163]
	s_add_i32 m0, s49, 0xc000
	ds_read_b128 v[202:205], v182
	ds_read_b128 v[206:209], v182 offset:1024
	ds_read_b128 v[210:213], v182 offset:2048
	ds_read_b128 v[214:217], v182 offset:3072
	ds_read_b128 v[218:221], v182 offset:4096
	ds_read_b128 v[222:225], v182 offset:5120
	ds_read_b128 v[226:229], v182 offset:6144
	ds_read_b128 v[230:233], v182 offset:7168
	global_load_lds_dwordx4 v[188:189], off
	v_lshl_add_u64 v[188:189], s[24:25], 0, v[164:165]
	s_add_i32 m0, s49, 0xe000
	s_nop 0
	global_load_lds_dwordx4 v[188:189], off
	s_waitcnt vmcnt(8)
	s_waitcnt lgkmcnt(0)
	s_barrier
	v_mfma_f32_16x16x32_bf16 v[126:129], v[130:133], v[202:205], v[126:129]
	v_mfma_f32_16x16x32_bf16 v[122:125], v[138:141], v[202:205], v[122:125]
	v_mfma_f32_16x16x32_bf16 v[110:113], v[130:133], v[210:213], v[110:113]
	v_mfma_f32_16x16x32_bf16 v[106:109], v[138:141], v[210:213], v[106:109]
	v_mfma_f32_16x16x32_bf16 v[94:97], v[130:133], v[218:221], v[94:97]
	v_mfma_f32_16x16x32_bf16 v[90:93], v[138:141], v[218:221], v[90:93]
	v_mfma_f32_16x16x32_bf16 v[76:79], v[130:133], v[226:229], v[76:79]
	v_mfma_f32_16x16x32_bf16 v[72:75], v[138:141], v[226:229], v[72:75]
	v_mfma_f32_16x16x32_bf16 v[126:129], v[134:137], v[206:209], v[126:129]
	v_mfma_f32_16x16x32_bf16 v[122:125], v[142:145], v[206:209], v[122:125]
	v_mfma_f32_16x16x32_bf16 v[110:113], v[134:137], v[214:217], v[110:113]
	v_mfma_f32_16x16x32_bf16 v[106:109], v[142:145], v[214:217], v[106:109]
	v_mfma_f32_16x16x32_bf16 v[94:97], v[134:137], v[222:225], v[94:97]
	v_mfma_f32_16x16x32_bf16 v[90:93], v[142:145], v[222:225], v[90:93]
	v_mfma_f32_16x16x32_bf16 v[76:79], v[134:137], v[230:233], v[76:79]
	v_mfma_f32_16x16x32_bf16 v[72:75], v[142:145], v[230:233], v[72:75]
	v_mfma_f32_16x16x32_bf16 v[118:121], v[166:169], v[202:205], v[118:121]
	v_mfma_f32_16x16x32_bf16 v[114:117], v[174:177], v[202:205], v[114:117]
	v_mfma_f32_16x16x32_bf16 v[102:105], v[166:169], v[210:213], v[102:105]
	v_mfma_f32_16x16x32_bf16 v[98:101], v[174:177], v[210:213], v[98:101]
	v_mfma_f32_16x16x32_bf16 v[86:89], v[166:169], v[218:221], v[86:89]
	v_mfma_f32_16x16x32_bf16 v[82:85], v[174:177], v[218:221], v[82:85]
	v_mfma_f32_16x16x32_bf16 v[68:71], v[166:169], v[226:229], v[68:71]
	v_mfma_f32_16x16x32_bf16 v[64:67], v[174:177], v[226:229], v[64:67]
	v_mfma_f32_16x16x32_bf16 v[118:121], v[170:173], v[206:209], v[118:121]
	v_mfma_f32_16x16x32_bf16 v[114:117], v[184:187], v[206:209], v[114:117]
	v_mfma_f32_16x16x32_bf16 v[102:105], v[170:173], v[214:217], v[102:105]
	v_mfma_f32_16x16x32_bf16 v[98:101], v[184:187], v[214:217], v[98:101]
	v_mfma_f32_16x16x32_bf16 v[86:89], v[170:173], v[222:225], v[86:89]
	v_mfma_f32_16x16x32_bf16 v[82:85], v[184:187], v[222:225], v[82:85]
	v_mfma_f32_16x16x32_bf16 v[68:71], v[170:173], v[230:233], v[68:71]
	v_mfma_f32_16x16x32_bf16 v[64:67], v[184:187], v[230:233], v[64:67]
	s_barrier
	s_add_i32 s67, s67, s48
	v_lshl_add_u64 v[188:189], s[26:27], 0, v[80:81]
	s_mov_b32 m0, s67
	ds_read_b128 v[202:205], v182 offset:16384
	ds_read_b128 v[206:209], v182 offset:17408
	ds_read_b128 v[210:213], v182 offset:18432
	ds_read_b128 v[214:217], v182 offset:19456
	ds_read_b128 v[218:221], v182 offset:20480
	ds_read_b128 v[222:225], v182 offset:21504
	ds_read_b128 v[226:229], v182 offset:22528
	ds_read_b128 v[230:233], v182 offset:23552
	global_load_lds_dwordx4 v[188:189], off
	s_add_i32 m0, s67, 0x2000
	s_add_u32 s68, s26, 0x40000
	v_lshl_add_u64 v[196:197], s[26:27], 0, v[150:151]
	s_addc_u32 s69, s27, 0
	s_add_i32 s67, s70, s48
	global_load_lds_dwordx4 v[196:197], off
	v_lshl_add_u64 v[198:199], s[68:69], 0, v[80:81]
	s_mov_b32 m0, s67
	v_lshl_add_u64 v[234:235], s[28:29], 0, v[148:149]
	global_load_lds_dwordx4 v[198:199], off
	v_lshl_add_u64 v[198:199], s[68:69], 0, v[150:151]
	s_add_i32 m0, s67, 0x2000
	s_nop 0
	global_load_lds_dwordx4 v[198:199], off
	v_lshl_add_u64 v[198:199], s[28:29], 0, v[146:147]
	s_mov_b32 m0, s49
	s_nop 0
	global_load_lds_dwordx4 v[198:199], off
	s_mov_b32 m0, s50
	s_nop 0
	global_load_lds_dwordx4 v[234:235], off
	s_waitcnt vmcnt(8)
	s_waitcnt lgkmcnt(0)
	s_barrier
; #define PG8_STAGE(bufoff, gbase, voff) do { _Pragma("unroll") for (int _i = 0; _i < 2; ++_i) \
;         __builtin_amdgcn_global_load_lds((const unsigned*)((const char*)(gbase) + (voff)[_i]), (PG8_LAS unsigned*)(lds + (bufoff) + ldsw + _i * 8192), 16, 0, 0); } while (0)
; #define PG8_LDA(dst, b, h) do { _Pragma("unroll") for (int m = 0; m < 4; ++m) _Pragma("unroll") for (int k = 0; k < 2; ++k) dst[m][k] = *(const PG8_LAS bf16x8*)(lds + PG8_SA(b, h) + aoff + m * 2048 + k * 1024); } while (0)
; #define PG8_LDB(dst, b, h) do { _Pragma("unroll") for (int n = 0; n < 2; ++n) _Pragma("unroll") for (int k = 0; k < 2; ++k) dst[n][k] = *(const PG8_LAS bf16x8*)(lds + PG8_SB(b, h) + boff + n * 2048 + k * 1024); } while (0)
; #define PG8_MMA(ai, bj, At, Bt) do { __builtin_amdgcn_s_setprio(1); _Pragma("unroll") for (int m = 0; m < 4; ++m) _Pragma("unroll") for (int n = 0; n < 2; ++n) _Pragma("unroll") for (int k = 0; k < 2; ++k) \
;         acc[ai][bj][m][n] = __builtin_amdgcn_mfma_f32_16x16x32_bf16(Bt[n][k], At[m][k], acc[ai][bj][m][n], 0, 0, 0); __builtin_amdgcn_s_setprio(0); } while (0)
; #define PG8_WAIT_V(n) asm volatile("s_waitcnt vmcnt(" #n ")" ::: "memory")
; #define PG8_WAIT_L(n) asm volatile("s_waitcnt lgkmcnt(" #n ")" ::: "memory")
; #define PG8_BAR __builtin_amdgcn_s_barrier()
; #define PG8_SCHED __builtin_amdgcn_sched_barrier(0)
; template <class Epi, class Sched, bool ALIGN_EPI = false, bool SP2 = false, bool HALFM = false>
; __device__ __forceinline__ void gemm_phase(PG8_LAS unsigned char* lds, const Gemm g, const Sched& S, const Epi& E) {
;     ...
;             PG8_WAIT_V(8); PG8_WAIT_L(0); PG8_BAR; if constexpr (!HALFM) { PG8_MMA(1, 0, At, B0); PG8_MMA(1, 1, At, B1); } PG8_BAR; PG8_SCHED;
;             PG8_LDB(B0, 1, 0); PG8_LDB(B1, 1, 1); PG8_SCHED; PG8_LDA(At, 1, 0); PG8_STAGE(PG8_SA(0, 1), a2 + hstep, voffA);
;             PG8_WAIT_V(8); PG8_WAIT_L(0); PG8_BAR; PG8_MMA(0, 0, At, B0); PG8_MMA(0, 1, At, B1); PG8_BAR; PG8_SCHED;
	v_mfma_f32_16x16x32_bf16 v[60:63], v[130:133], v[202:205], v[60:63]
	v_mfma_f32_16x16x32_bf16 v[56:59], v[138:141], v[202:205], v[56:59]
	v_mfma_f32_16x16x32_bf16 v[44:47], v[130:133], v[210:213], v[44:47]
	v_mfma_f32_16x16x32_bf16 v[40:43], v[138:141], v[210:213], v[40:43]
	v_mfma_f32_16x16x32_bf16 v[28:31], v[130:133], v[218:221], v[28:31]
	v_mfma_f32_16x16x32_bf16 v[24:27], v[138:141], v[218:221], v[24:27]
	v_mfma_f32_16x16x32_bf16 v[12:15], v[130:133], v[226:229], v[12:15]
	v_mfma_f32_16x16x32_bf16 v[8:11], v[138:141], v[226:229], v[8:11]
	v_mfma_f32_16x16x32_bf16 v[60:63], v[134:137], v[206:209], v[60:63]
	v_mfma_f32_16x16x32_bf16 v[56:59], v[142:145], v[206:209], v[56:59]
	v_mfma_f32_16x16x32_bf16 v[44:47], v[134:137], v[214:217], v[44:47]
	v_mfma_f32_16x16x32_bf16 v[40:43], v[142:145], v[214:217], v[40:43]
	v_mfma_f32_16x16x32_bf16 v[28:31], v[134:137], v[222:225], v[28:31]
	v_mfma_f32_16x16x32_bf16 v[24:27], v[142:145], v[222:225], v[24:27]
	v_mfma_f32_16x16x32_bf16 v[12:15], v[134:137], v[230:233], v[12:15]
	v_mfma_f32_16x16x32_bf16 v[8:11], v[142:145], v[230:233], v[8:11]
	v_mfma_f32_16x16x32_bf16 v[52:55], v[166:169], v[202:205], v[52:55]
	v_mfma_f32_16x16x32_bf16 v[48:51], v[174:177], v[202:205], v[48:51]
	v_mfma_f32_16x16x32_bf16 v[36:39], v[166:169], v[210:213], v[36:39]
	v_mfma_f32_16x16x32_bf16 v[32:35], v[174:177], v[210:213], v[32:35]
	v_mfma_f32_16x16x32_bf16 v[20:23], v[166:169], v[218:221], v[20:23]
	v_mfma_f32_16x16x32_bf16 v[16:19], v[174:177], v[218:221], v[16:19]
	v_mfma_f32_16x16x32_bf16 v[4:7], v[166:169], v[226:229], v[4:7]
	v_mfma_f32_16x16x32_bf16 v[0:3], v[174:177], v[226:229], v[0:3]
	v_mfma_f32_16x16x32_bf16 v[52:55], v[170:173], v[206:209], v[52:55]
	v_mfma_f32_16x16x32_bf16 v[48:51], v[184:187], v[206:209], v[48:51]
	v_mfma_f32_16x16x32_bf16 v[36:39], v[170:173], v[214:217], v[36:39]
	v_mfma_f32_16x16x32_bf16 v[32:35], v[184:187], v[214:217], v[32:35]
	v_mfma_f32_16x16x32_bf16 v[20:23], v[170:173], v[222:225], v[20:23]
	v_mfma_f32_16x16x32_bf16 v[16:19], v[184:187], v[222:225], v[16:19]
	v_mfma_f32_16x16x32_bf16 v[4:7], v[170:173], v[230:233], v[4:7]
	v_mfma_f32_16x16x32_bf16 v[0:3], v[184:187], v[230:233], v[0:3]
	s_barrier
	s_add_i32 s67, 0, 0x18000
	s_add_i32 s68, 0, 0x1c000
	v_add_u32_e32 v142, s67, v179
	v_add_u32_e32 v183, s68, v179
	ds_read_b128 v[130:133], v142
	ds_read_b128 v[134:137], v142 offset:1024
	ds_read_b128 v[138:141], v142 offset:2048
	ds_read_b128 v[142:145], v142 offset:3072
	ds_read_b128 v[166:169], v183
	ds_read_b128 v[170:173], v183 offset:1024
	ds_read_b128 v[174:177], v183 offset:2048
	ds_read_b128 v[184:187], v183 offset:3072
	s_add_u32 s28, s28, 0x40000
	s_addc_u32 s29, s29, 0
	s_mov_b32 m0, s51
	v_lshl_add_u64 v[236:237], s[28:29], 0, v[146:147]
	ds_read_b128 v[202:205], v182 offset:32768
	ds_read_b128 v[206:209], v182 offset:33792
	ds_read_b128 v[210:213], v182 offset:34816
	ds_read_b128 v[214:217], v182 offset:35840
	ds_read_b128 v[218:221], v182 offset:36864
	ds_read_b128 v[222:225], v182 offset:37888
	ds_read_b128 v[226:229], v182 offset:38912
	ds_read_b128 v[230:233], v182 offset:39936
	global_load_lds_dwordx4 v[236:237], off
	v_lshl_add_u64 v[236:237], s[28:29], 0, v[148:149]
	s_mov_b32 m0, s52
	s_nop 0
	global_load_lds_dwordx4 v[236:237], off
	s_waitcnt vmcnt(8)
	s_waitcnt lgkmcnt(0)
	s_barrier
	v_mfma_f32_16x16x32_bf16 v[126:129], v[130:133], v[202:205], v[126:129]
	v_mfma_f32_16x16x32_bf16 v[122:125], v[138:141], v[202:205], v[122:125]
	v_mfma_f32_16x16x32_bf16 v[110:113], v[130:133], v[210:213], v[110:113]
	v_mfma_f32_16x16x32_bf16 v[106:109], v[138:141], v[210:213], v[106:109]
	v_mfma_f32_16x16x32_bf16 v[94:97], v[130:133], v[218:221], v[94:97]
	v_mfma_f32_16x16x32_bf16 v[90:93], v[138:141], v[218:221], v[90:93]
	v_mfma_f32_16x16x32_bf16 v[76:79], v[130:133], v[226:229], v[76:79]
	v_mfma_f32_16x16x32_bf16 v[72:75], v[138:141], v[226:229], v[72:75]
	v_mfma_f32_16x16x32_bf16 v[126:129], v[134:137], v[206:209], v[126:129]
	v_mfma_f32_16x16x32_bf16 v[122:125], v[142:145], v[206:209], v[122:125]
	v_mfma_f32_16x16x32_bf16 v[110:113], v[134:137], v[214:217], v[110:113]
	v_mfma_f32_16x16x32_bf16 v[106:109], v[142:145], v[214:217], v[106:109]
	v_mfma_f32_16x16x32_bf16 v[94:97], v[134:137], v[222:225], v[94:97]
	v_mfma_f32_16x16x32_bf16 v[90:93], v[142:145], v[222:225], v[90:93]
	v_mfma_f32_16x16x32_bf16 v[76:79], v[134:137], v[230:233], v[76:79]
	v_mfma_f32_16x16x32_bf16 v[72:75], v[142:145], v[230:233], v[72:75]
	v_mfma_f32_16x16x32_bf16 v[118:121], v[166:169], v[202:205], v[118:121]
	v_mfma_f32_16x16x32_bf16 v[114:117], v[174:177], v[202:205], v[114:117]
	v_mfma_f32_16x16x32_bf16 v[102:105], v[166:169], v[210:213], v[102:105]
	v_mfma_f32_16x16x32_bf16 v[98:101], v[174:177], v[210:213], v[98:101]
	v_mfma_f32_16x16x32_bf16 v[86:89], v[166:169], v[218:221], v[86:89]
	v_mfma_f32_16x16x32_bf16 v[82:85], v[174:177], v[218:221], v[82:85]
	v_mfma_f32_16x16x32_bf16 v[68:71], v[166:169], v[226:229], v[68:71]
	v_mfma_f32_16x16x32_bf16 v[64:67], v[174:177], v[226:229], v[64:67]
	v_mfma_f32_16x16x32_bf16 v[118:121], v[170:173], v[206:209], v[118:121]
	v_mfma_f32_16x16x32_bf16 v[114:117], v[184:187], v[206:209], v[114:117]
	v_mfma_f32_16x16x32_bf16 v[102:105], v[170:173], v[214:217], v[102:105]
	v_mfma_f32_16x16x32_bf16 v[98:101], v[184:187], v[214:217], v[98:101]
	v_mfma_f32_16x16x32_bf16 v[86:89], v[170:173], v[222:225], v[86:89]
	v_mfma_f32_16x16x32_bf16 v[82:85], v[184:187], v[222:225], v[82:85]
	v_mfma_f32_16x16x32_bf16 v[68:71], v[170:173], v[230:233], v[68:71]
	v_mfma_f32_16x16x32_bf16 v[64:67], v[184:187], v[230:233], v[64:67]
	s_barrier
; #define PG8_STAGE(bufoff, gbase, voff) do { _Pragma("unroll") for (int _i = 0; _i < 2; ++_i) \
;         __builtin_amdgcn_global_load_lds((const unsigned*)((const char*)(gbase) + (voff)[_i]), (PG8_LAS unsigned*)(lds + (bufoff) + ldsw + _i * 8192), 16, 0, 0); } while (0)
; #define PG8_LDA(dst, b, h) do { _Pragma("unroll") for (int m = 0; m < 4; ++m) _Pragma("unroll") for (int k = 0; k < 2; ++k) dst[m][k] = *(const PG8_LAS bf16x8*)(lds + PG8_SA(b, h) + aoff + m * 2048 + k * 1024); } while (0)
; #define PG8_MMA(ai, bj, At, Bt) do { __builtin_amdgcn_s_setprio(1); _Pragma("unroll") for (int m = 0; m < 4; ++m) _Pragma("unroll") for (int n = 0; n < 2; ++n) _Pragma("unroll") for (int k = 0; k < 2; ++k) \
;         acc[ai][bj][m][n] = __builtin_amdgcn_mfma_f32_16x16x32_bf16(Bt[n][k], At[m][k], acc[ai][bj][m][n], 0, 0, 0); __builtin_amdgcn_s_setprio(0); } while (0)
; #define PG8_WAIT_V(n) asm volatile("s_waitcnt vmcnt(" #n ")" ::: "memory")
; #define PG8_WAIT_L(n) asm volatile("s_waitcnt lgkmcnt(" #n ")" ::: "memory")
; #define PG8_BAR __builtin_amdgcn_s_barrier()
; #define PG8_SCHED __builtin_amdgcn_sched_barrier(0)
; template <class Epi, class Sched, bool ALIGN_EPI = false, bool SP2 = false, bool HALFM = false>
; __device__ __forceinline__ void gemm_phase(PG8_LAS unsigned char* lds, const Gemm g, const Sched& S, const Epi& E) {
;     ...
;             if constexpr (!HALFM) PG8_LDA(At, 1, 1); PG8_STAGE(PG8_SB(1, 0), b3, voffB); PG8_STAGE(PG8_SB(1, 1), b3 + hstep, voffB); PG8_STAGE(PG8_SA(1, 0), a3, voffA);
;             PG8_WAIT_V(8); PG8_WAIT_L(0); PG8_BAR; if constexpr (!HALFM) { PG8_MMA(1, 0, At, B0); PG8_MMA(1, 1, At, B1); } PG8_BAR; PG8_SCHED;
	s_add_i32 s28, s67, s48
	v_lshl_add_u64 v[188:189], v[188:189], 0, s[82:83]
	s_mov_b32 m0, s28
	ds_read_b128 v[202:205], v182 offset:49152
	ds_read_b128 v[206:209], v182 offset:50176
	ds_read_b128 v[210:213], v182 offset:51200
	ds_read_b128 v[214:217], v182 offset:52224
	ds_read_b128 v[218:221], v182 offset:53248
	ds_read_b128 v[222:225], v182 offset:54272
	ds_read_b128 v[226:229], v182 offset:55296
	ds_read_b128 v[230:233], v182 offset:56320
	global_load_lds_dwordx4 v[188:189], off
	s_add_i32 m0, s28, 0x2000
	s_add_u32 s26, s26, 0x40080
	v_lshl_add_u64 v[188:189], v[196:197], 0, s[82:83]
	s_addc_u32 s27, s27, 0
	s_add_i32 s28, s68, s48
	global_load_lds_dwordx4 v[188:189], off
	v_lshl_add_u64 v[188:189], s[26:27], 0, v[80:81]
	s_mov_b32 m0, s28
	s_nop 0
	global_load_lds_dwordx4 v[188:189], off
	v_lshl_add_u64 v[188:189], s[26:27], 0, v[150:151]
	s_add_i32 m0, s28, 0x2000
	s_nop 0
	global_load_lds_dwordx4 v[188:189], off
	v_lshl_add_u64 v[188:189], v[198:199], 0, s[82:83]
	s_mov_b32 m0, s53
	s_nop 0
	global_load_lds_dwordx4 v[188:189], off
	v_lshl_add_u64 v[188:189], v[234:235], 0, s[82:83]
	s_mov_b32 m0, s54
	s_nop 0
	global_load_lds_dwordx4 v[188:189], off
	s_waitcnt vmcnt(8)
	s_waitcnt lgkmcnt(0)
	s_barrier
	v_mfma_f32_16x16x32_bf16 v[60:63], v[130:133], v[202:205], v[60:63]
	v_mfma_f32_16x16x32_bf16 v[56:59], v[138:141], v[202:205], v[56:59]
	v_mfma_f32_16x16x32_bf16 v[44:47], v[130:133], v[210:213], v[44:47]
	v_mfma_f32_16x16x32_bf16 v[40:43], v[138:141], v[210:213], v[40:43]
	v_mfma_f32_16x16x32_bf16 v[28:31], v[130:133], v[218:221], v[28:31]
	v_mfma_f32_16x16x32_bf16 v[24:27], v[138:141], v[218:221], v[24:27]
	v_mfma_f32_16x16x32_bf16 v[12:15], v[130:133], v[226:229], v[12:15]
	v_mfma_f32_16x16x32_bf16 v[8:11], v[138:141], v[226:229], v[8:11]
	v_mfma_f32_16x16x32_bf16 v[60:63], v[134:137], v[206:209], v[60:63]
	v_mfma_f32_16x16x32_bf16 v[56:59], v[142:145], v[206:209], v[56:59]
	v_mfma_f32_16x16x32_bf16 v[44:47], v[134:137], v[214:217], v[44:47]
	v_mfma_f32_16x16x32_bf16 v[40:43], v[142:145], v[214:217], v[40:43]
	v_mfma_f32_16x16x32_bf16 v[28:31], v[134:137], v[222:225], v[28:31]
	v_mfma_f32_16x16x32_bf16 v[24:27], v[142:145], v[222:225], v[24:27]
	v_mfma_f32_16x16x32_bf16 v[12:15], v[134:137], v[230:233], v[12:15]
	v_mfma_f32_16x16x32_bf16 v[8:11], v[142:145], v[230:233], v[8:11]
	v_mfma_f32_16x16x32_bf16 v[52:55], v[166:169], v[202:205], v[52:55]
	v_mfma_f32_16x16x32_bf16 v[48:51], v[174:177], v[202:205], v[48:51]
	v_mfma_f32_16x16x32_bf16 v[36:39], v[166:169], v[210:213], v[36:39]
	v_mfma_f32_16x16x32_bf16 v[32:35], v[174:177], v[210:213], v[32:35]
	v_mfma_f32_16x16x32_bf16 v[20:23], v[166:169], v[218:221], v[20:23]
	v_mfma_f32_16x16x32_bf16 v[16:19], v[174:177], v[218:221], v[16:19]
	v_mfma_f32_16x16x32_bf16 v[4:7], v[166:169], v[226:229], v[4:7]
	v_mfma_f32_16x16x32_bf16 v[0:3], v[174:177], v[226:229], v[0:3]
	v_mfma_f32_16x16x32_bf16 v[52:55], v[170:173], v[206:209], v[52:55]
	v_mfma_f32_16x16x32_bf16 v[48:51], v[184:187], v[206:209], v[48:51]
	v_mfma_f32_16x16x32_bf16 v[36:39], v[170:173], v[214:217], v[36:39]
	v_mfma_f32_16x16x32_bf16 v[32:35], v[184:187], v[214:217], v[32:35]
	v_mfma_f32_16x16x32_bf16 v[20:23], v[170:173], v[222:225], v[20:23]
	v_mfma_f32_16x16x32_bf16 v[16:19], v[184:187], v[222:225], v[16:19]
	v_mfma_f32_16x16x32_bf16 v[4:7], v[170:173], v[230:233], v[4:7]
	v_mfma_f32_16x16x32_bf16 v[0:3], v[184:187], v[230:233], v[0:3]
	s_barrier
	s_add_i32 s66, s66, 2
	s_add_u32 s24, s24, 0x100
	s_addc_u32 s25, s25, 0
	s_add_u32 s64, s64, 0x100
	s_addc_u32 s65, s65, 0
	s_cmp_gt_u32 s66, 13
	s_cbranch_scc1 .LBB0_417

; #define PG8_STAGE(bufoff, gbase, voff) do { _Pragma("unroll") for (int _i = 0; _i < 2; ++_i) \
;         __builtin_amdgcn_global_load_lds((const unsigned*)((const char*)(gbase) + (voff)[_i]), (PG8_LAS unsigned*)(lds + (bufoff) + ldsw + _i * 8192), 16, 0, 0); } while (0)
; #define PG8_LDA(dst, b, h) do { _Pragma("unroll") for (int m = 0; m < 4; ++m) _Pragma("unroll") for (int k = 0; k < 2; ++k) dst[m][k] = *(const PG8_LAS bf16x8*)(lds + PG8_SA(b, h) + aoff + m * 2048 + k * 1024); } while (0)
; #define PG8_LDB(dst, b, h) do { _Pragma("unroll") for (int n = 0; n < 2; ++n) _Pragma("unroll") for (int k = 0; k < 2; ++k) dst[n][k] = *(const PG8_LAS bf16x8*)(lds + PG8_SB(b, h) + boff + n * 2048 + k * 1024); } while (0)
; #define PG8_MMA(ai, bj, At, Bt) do { __builtin_amdgcn_s_setprio(1); _Pragma("unroll") for (int m = 0; m < 4; ++m) _Pragma("unroll") for (int n = 0; n < 2; ++n) _Pragma("unroll") for (int k = 0; k < 2; ++k) \
;         acc[ai][bj][m][n] = __builtin_amdgcn_mfma_f32_16x16x32_bf16(Bt[n][k], At[m][k], acc[ai][bj][m][n], 0, 0, 0); __builtin_amdgcn_s_setprio(0); } while (0)
; #define PG8_WAIT_V(n) asm volatile("s_waitcnt vmcnt(" #n ")" ::: "memory")
; #define PG8_BAR __builtin_amdgcn_s_barrier()
; template <class Epi, class Sched, bool ALIGN_EPI = false, bool SP2 = false, bool HALFM = false>
; __device__ __forceinline__ void gemm_phase(PG8_LAS unsigned char* lds, const Gemm g, const Sched& S, const Epi& E) {
;     ...
;             const bool last = (t == nt - 2);
;             const char* a1 = cA + (size_t)(t + 1) * kstep;
;             const char* a2 = last ? nA : cA + (size_t)(t + 2) * kstep; const char* b2 = last ? nB : cB + (size_t)(t + 2) * kstep;
;             const char* a3 = a2 + kstep; const char* b3 = b2 + kstep;
;             if (last && has_next) S.a_ready(nxt);
;             if constexpr (SP2) {
;             PG8_LDB(B0, 0, 0); PG8_LDB(B1, 0, 1); PG8_SCHED; PG8_LDA(At, 0, 0); PG8_STAGE(PG8_SA(1, 1), a1 + hstep, voffA);
;             PG8_WAIT_V(8); PG8_WAIT_L(0); PG8_BAR; PG8_MMA(0, 0, At, B0); PG8_MMA(0, 1, At, B1); PG8_BAR; PG8_SCHED;
;             if constexpr (!HALFM) PG8_LDA(At, 0, 1); PG8_STAGE(PG8_SB(0, 0), b2, voffB); PG8_STAGE(PG8_SB(0, 1), b2 + hstep, voffB); PG8_STAGE(PG8_SA(0, 0), a2, voffA);
;             PG8_WAIT_V(8); PG8_WAIT_L(0); PG8_BAR; if constexpr (!HALFM) { PG8_MMA(1, 0, At, B0); PG8_MMA(1, 1, At, B1); } PG8_BAR; PG8_SCHED;
.LBB0_1165:
	s_add_u32 s20, s18, 0xfffc0080
	s_addc_u32 s21, s19, -1
	s_add_i32 s57, 0, 0x10000
	s_cmp_eq_u32 s56, 12
	s_cselect_b32 s23, s13, s21
	s_cselect_b32 s22, s52, s20
	s_cselect_b32 s21, s11, s55
	s_cselect_b32 s20, s53, s54
	s_add_i32 s60, 0, 0x14000
	v_add_u32_e32 v142, s57, v189
	v_add_u32_e32 v174, s60, v189
	ds_read_b128 v[130:133], v142
	ds_read_b128 v[134:137], v142 offset:1024
	ds_read_b128 v[138:141], v142 offset:2048
	ds_read_b128 v[142:145], v142 offset:3072
	ds_read_b128 v[146:149], v174
	ds_read_b128 v[150:153], v174 offset:1024
	ds_read_b128 v[170:173], v174 offset:2048
	ds_read_b128 v[174:177], v174 offset:3072
	v_lshl_add_u64 v[186:187], s[18:19], 0, v[166:167]
	s_add_i32 m0, s27, 0xc000
	ds_read_b128 v[178:181], v203
	ds_read_b128 v[182:185], v203 offset:1024
	ds_read_b128 v[196:199], v203 offset:2048
	ds_read_b128 v[204:207], v203 offset:3072
	ds_read_b128 v[208:211], v203 offset:4096
	ds_read_b128 v[212:215], v203 offset:5120
	ds_read_b128 v[216:219], v203 offset:6144
	ds_read_b128 v[220:223], v203 offset:7168
	global_load_lds_dwordx4 v[186:187], off
	v_lshl_add_u64 v[186:187], s[18:19], 0, v[168:169]
	s_add_i32 m0, s27, 0xe000
	s_nop 0
	global_load_lds_dwordx4 v[186:187], off
	s_waitcnt vmcnt(8)
	s_waitcnt lgkmcnt(0)
	s_barrier
	v_mfma_f32_16x16x32_bf16 v[126:129], v[130:133], v[178:181], v[126:129]
	v_mfma_f32_16x16x32_bf16 v[122:125], v[138:141], v[178:181], v[122:125]
	v_mfma_f32_16x16x32_bf16 v[110:113], v[130:133], v[196:199], v[110:113]
	v_mfma_f32_16x16x32_bf16 v[106:109], v[138:141], v[196:199], v[106:109]
	v_mfma_f32_16x16x32_bf16 v[94:97], v[130:133], v[208:211], v[94:97]
	v_mfma_f32_16x16x32_bf16 v[90:93], v[138:141], v[208:211], v[90:93]
	v_mfma_f32_16x16x32_bf16 v[76:79], v[130:133], v[216:219], v[76:79]
	v_mfma_f32_16x16x32_bf16 v[72:75], v[138:141], v[216:219], v[72:75]
	v_mfma_f32_16x16x32_bf16 v[126:129], v[134:137], v[182:185], v[126:129]
	v_mfma_f32_16x16x32_bf16 v[122:125], v[142:145], v[182:185], v[122:125]
	v_mfma_f32_16x16x32_bf16 v[110:113], v[134:137], v[204:207], v[110:113]
	v_mfma_f32_16x16x32_bf16 v[106:109], v[142:145], v[204:207], v[106:109]
	v_mfma_f32_16x16x32_bf16 v[94:97], v[134:137], v[212:215], v[94:97]
	v_mfma_f32_16x16x32_bf16 v[90:93], v[142:145], v[212:215], v[90:93]
	v_mfma_f32_16x16x32_bf16 v[76:79], v[134:137], v[220:223], v[76:79]
	v_mfma_f32_16x16x32_bf16 v[72:75], v[142:145], v[220:223], v[72:75]
	v_mfma_f32_16x16x32_bf16 v[118:121], v[146:149], v[178:181], v[118:121]
	v_mfma_f32_16x16x32_bf16 v[114:117], v[170:173], v[178:181], v[114:117]
	v_mfma_f32_16x16x32_bf16 v[102:105], v[146:149], v[196:199], v[102:105]
	v_mfma_f32_16x16x32_bf16 v[98:101], v[170:173], v[196:199], v[98:101]
	v_mfma_f32_16x16x32_bf16 v[86:89], v[146:149], v[208:211], v[86:89]
	v_mfma_f32_16x16x32_bf16 v[82:85], v[170:173], v[208:211], v[82:85]
	v_mfma_f32_16x16x32_bf16 v[68:71], v[146:149], v[216:219], v[68:71]
	v_mfma_f32_16x16x32_bf16 v[64:67], v[170:173], v[216:219], v[64:67]
	v_mfma_f32_16x16x32_bf16 v[118:121], v[150:153], v[182:185], v[118:121]
	v_mfma_f32_16x16x32_bf16 v[114:117], v[174:177], v[182:185], v[114:117]
	v_mfma_f32_16x16x32_bf16 v[102:105], v[150:153], v[204:207], v[102:105]
	v_mfma_f32_16x16x32_bf16 v[98:101], v[174:177], v[204:207], v[98:101]
	v_mfma_f32_16x16x32_bf16 v[86:89], v[150:153], v[212:215], v[86:89]
	v_mfma_f32_16x16x32_bf16 v[82:85], v[174:177], v[212:215], v[82:85]
	v_mfma_f32_16x16x32_bf16 v[68:71], v[150:153], v[220:223], v[68:71]
	v_mfma_f32_16x16x32_bf16 v[64:67], v[174:177], v[220:223], v[64:67]
	s_barrier
	s_add_i32 s57, s57, s26
	v_lshl_add_u64 v[186:187], s[20:21], 0, v[80:81]
	s_mov_b32 m0, s57
	ds_read_b128 v[178:181], v203 offset:16384
	ds_read_b128 v[182:185], v203 offset:17408
	ds_read_b128 v[196:199], v203 offset:18432
	ds_read_b128 v[204:207], v203 offset:19456
	ds_read_b128 v[208:211], v203 offset:20480
	ds_read_b128 v[212:215], v203 offset:21504
	ds_read_b128 v[216:219], v203 offset:22528
	ds_read_b128 v[220:223], v203 offset:23552
	global_load_lds_dwordx4 v[186:187], off
	s_add_i32 m0, s57, 0x2000
	s_add_u32 s58, s20, 0x40000
	v_lshl_add_u64 v[224:225], s[20:21], 0, v[160:161]
	s_addc_u32 s59, s21, 0
	s_add_i32 s57, s60, s26
	global_load_lds_dwordx4 v[224:225], off
	v_lshl_add_u64 v[226:227], s[58:59], 0, v[80:81]
	s_mov_b32 m0, s57
	v_lshl_add_u64 v[228:229], s[22:23], 0, v[162:163]
	global_load_lds_dwordx4 v[226:227], off
	v_lshl_add_u64 v[226:227], s[58:59], 0, v[160:161]
	s_add_i32 m0, s57, 0x2000
	s_nop 0
	global_load_lds_dwordx4 v[226:227], off
	v_lshl_add_u64 v[226:227], s[22:23], 0, v[164:165]
	s_mov_b32 m0, s27
	s_nop 0
	global_load_lds_dwordx4 v[226:227], off
	s_mov_b32 m0, s28
	s_nop 0
	global_load_lds_dwordx4 v[228:229], off
	s_waitcnt vmcnt(8)
	s_waitcnt lgkmcnt(0)
	s_barrier
; #define PG8_STAGE(bufoff, gbase, voff) do { _Pragma("unroll") for (int _i = 0; _i < 2; ++_i) \
;         __builtin_amdgcn_global_load_lds((const unsigned*)((const char*)(gbase) + (voff)[_i]), (PG8_LAS unsigned*)(lds + (bufoff) + ldsw + _i * 8192), 16, 0, 0); } while (0)
; #define PG8_LDA(dst, b, h) do { _Pragma("unroll") for (int m = 0; m < 4; ++m) _Pragma("unroll") for (int k = 0; k < 2; ++k) dst[m][k] = *(const PG8_LAS bf16x8*)(lds + PG8_SA(b, h) + aoff + m * 2048 + k * 1024); } while (0)
; #define PG8_LDB(dst, b, h) do { _Pragma("unroll") for (int n = 0; n < 2; ++n) _Pragma("unroll") for (int k = 0; k < 2; ++k) dst[n][k] = *(const PG8_LAS bf16x8*)(lds + PG8_SB(b, h) + boff + n * 2048 + k * 1024); } while (0)
; #define PG8_MMA(ai, bj, At, Bt) do { __builtin_amdgcn_s_setprio(1); _Pragma("unroll") for (int m = 0; m < 4; ++m) _Pragma("unroll") for (int n = 0; n < 2; ++n) _Pragma("unroll") for (int k = 0; k < 2; ++k) \
;         acc[ai][bj][m][n] = __builtin_amdgcn_mfma_f32_16x16x32_bf16(Bt[n][k], At[m][k], acc[ai][bj][m][n], 0, 0, 0); __builtin_amdgcn_s_setprio(0); } while (0)
; #define PG8_WAIT_V(n) asm volatile("s_waitcnt vmcnt(" #n ")" ::: "memory")
; #define PG8_WAIT_L(n) asm volatile("s_waitcnt lgkmcnt(" #n ")" ::: "memory")
; #define PG8_BAR __builtin_amdgcn_s_barrier()
; #define PG8_SCHED __builtin_amdgcn_sched_barrier(0)
; template <class Epi, class Sched, bool ALIGN_EPI = false, bool SP2 = false, bool HALFM = false>
; __device__ __forceinline__ void gemm_phase(PG8_LAS unsigned char* lds, const Gemm g, const Sched& S, const Epi& E) {
;     ...
;             PG8_WAIT_V(8); PG8_WAIT_L(0); PG8_BAR; if constexpr (!HALFM) { PG8_MMA(1, 0, At, B0); PG8_MMA(1, 1, At, B1); } PG8_BAR; PG8_SCHED;
;             PG8_LDB(B0, 1, 0); PG8_LDB(B1, 1, 1); PG8_SCHED; PG8_LDA(At, 1, 0); PG8_STAGE(PG8_SA(0, 1), a2 + hstep, voffA);
;             PG8_WAIT_V(8); PG8_WAIT_L(0); PG8_BAR; PG8_MMA(0, 0, At, B0); PG8_MMA(0, 1, At, B1); PG8_BAR; PG8_SCHED;
	v_mfma_f32_16x16x32_bf16 v[60:63], v[130:133], v[178:181], v[60:63]
	v_mfma_f32_16x16x32_bf16 v[56:59], v[138:141], v[178:181], v[56:59]
	v_mfma_f32_16x16x32_bf16 v[44:47], v[130:133], v[196:199], v[44:47]
	v_mfma_f32_16x16x32_bf16 v[40:43], v[138:141], v[196:199], v[40:43]
	v_mfma_f32_16x16x32_bf16 v[28:31], v[130:133], v[208:211], v[28:31]
	v_mfma_f32_16x16x32_bf16 v[24:27], v[138:141], v[208:211], v[24:27]
	v_mfma_f32_16x16x32_bf16 v[12:15], v[130:133], v[216:219], v[12:15]
	v_mfma_f32_16x16x32_bf16 v[8:11], v[138:141], v[216:219], v[8:11]
	v_mfma_f32_16x16x32_bf16 v[60:63], v[134:137], v[182:185], v[60:63]
	v_mfma_f32_16x16x32_bf16 v[56:59], v[142:145], v[182:185], v[56:59]
	v_mfma_f32_16x16x32_bf16 v[44:47], v[134:137], v[204:207], v[44:47]
	v_mfma_f32_16x16x32_bf16 v[40:43], v[142:145], v[204:207], v[40:43]
	v_mfma_f32_16x16x32_bf16 v[28:31], v[134:137], v[212:215], v[28:31]
	v_mfma_f32_16x16x32_bf16 v[24:27], v[142:145], v[212:215], v[24:27]
	v_mfma_f32_16x16x32_bf16 v[12:15], v[134:137], v[220:223], v[12:15]
	v_mfma_f32_16x16x32_bf16 v[8:11], v[142:145], v[220:223], v[8:11]
	v_mfma_f32_16x16x32_bf16 v[52:55], v[146:149], v[178:181], v[52:55]
	v_mfma_f32_16x16x32_bf16 v[48:51], v[170:173], v[178:181], v[48:51]
	v_mfma_f32_16x16x32_bf16 v[36:39], v[146:149], v[196:199], v[36:39]
	v_mfma_f32_16x16x32_bf16 v[32:35], v[170:173], v[196:199], v[32:35]
	v_mfma_f32_16x16x32_bf16 v[20:23], v[146:149], v[208:211], v[20:23]
	v_mfma_f32_16x16x32_bf16 v[16:19], v[170:173], v[208:211], v[16:19]
	v_mfma_f32_16x16x32_bf16 v[4:7], v[146:149], v[216:219], v[4:7]
	v_mfma_f32_16x16x32_bf16 v[0:3], v[170:173], v[216:219], v[0:3]
	v_mfma_f32_16x16x32_bf16 v[52:55], v[150:153], v[182:185], v[52:55]
	v_mfma_f32_16x16x32_bf16 v[48:51], v[174:177], v[182:185], v[48:51]
	v_mfma_f32_16x16x32_bf16 v[36:39], v[150:153], v[204:207], v[36:39]
	v_mfma_f32_16x16x32_bf16 v[32:35], v[174:177], v[204:207], v[32:35]
	v_mfma_f32_16x16x32_bf16 v[20:23], v[150:153], v[212:215], v[20:23]
	v_mfma_f32_16x16x32_bf16 v[16:19], v[174:177], v[212:215], v[16:19]
	v_mfma_f32_16x16x32_bf16 v[4:7], v[150:153], v[220:223], v[4:7]
	v_mfma_f32_16x16x32_bf16 v[0:3], v[174:177], v[220:223], v[0:3]
	s_barrier
	s_add_i32 s57, 0, 0x18000
	s_add_i32 s58, 0, 0x1c000
	v_add_u32_e32 v142, s57, v189
	v_add_u32_e32 v174, s58, v189
	ds_read_b128 v[130:133], v142
	ds_read_b128 v[134:137], v142 offset:1024
	ds_read_b128 v[138:141], v142 offset:2048
	ds_read_b128 v[142:145], v142 offset:3072
	ds_read_b128 v[146:149], v174
	ds_read_b128 v[150:153], v174 offset:1024
	ds_read_b128 v[170:173], v174 offset:2048
	ds_read_b128 v[174:177], v174 offset:3072
	s_add_u32 s22, s22, 0x40000
	s_addc_u32 s23, s23, 0
	s_mov_b32 m0, s29
	v_lshl_add_u64 v[230:231], s[22:23], 0, v[164:165]
	ds_read_b128 v[178:181], v203 offset:32768
	ds_read_b128 v[182:185], v203 offset:33792
	ds_read_b128 v[196:199], v203 offset:34816
	ds_read_b128 v[204:207], v203 offset:35840
	ds_read_b128 v[208:211], v203 offset:36864
	ds_read_b128 v[212:215], v203 offset:37888
	ds_read_b128 v[216:219], v203 offset:38912
	ds_read_b128 v[220:223], v203 offset:39936
	global_load_lds_dwordx4 v[230:231], off
	v_lshl_add_u64 v[230:231], s[22:23], 0, v[162:163]
	s_mov_b32 m0, s45
	s_nop 0
	global_load_lds_dwordx4 v[230:231], off
	s_waitcnt vmcnt(8)
	s_waitcnt lgkmcnt(0)
	s_barrier
	v_mfma_f32_16x16x32_bf16 v[126:129], v[130:133], v[178:181], v[126:129]
	v_mfma_f32_16x16x32_bf16 v[122:125], v[138:141], v[178:181], v[122:125]
	v_mfma_f32_16x16x32_bf16 v[110:113], v[130:133], v[196:199], v[110:113]
	v_mfma_f32_16x16x32_bf16 v[106:109], v[138:141], v[196:199], v[106:109]
	v_mfma_f32_16x16x32_bf16 v[94:97], v[130:133], v[208:211], v[94:97]
	v_mfma_f32_16x16x32_bf16 v[90:93], v[138:141], v[208:211], v[90:93]
	v_mfma_f32_16x16x32_bf16 v[76:79], v[130:133], v[216:219], v[76:79]
	v_mfma_f32_16x16x32_bf16 v[72:75], v[138:141], v[216:219], v[72:75]
	v_mfma_f32_16x16x32_bf16 v[126:129], v[134:137], v[182:185], v[126:129]
	v_mfma_f32_16x16x32_bf16 v[122:125], v[142:145], v[182:185], v[122:125]
	v_mfma_f32_16x16x32_bf16 v[110:113], v[134:137], v[204:207], v[110:113]
	v_mfma_f32_16x16x32_bf16 v[106:109], v[142:145], v[204:207], v[106:109]
	v_mfma_f32_16x16x32_bf16 v[94:97], v[134:137], v[212:215], v[94:97]
	v_mfma_f32_16x16x32_bf16 v[90:93], v[142:145], v[212:215], v[90:93]
	v_mfma_f32_16x16x32_bf16 v[76:79], v[134:137], v[220:223], v[76:79]
	v_mfma_f32_16x16x32_bf16 v[72:75], v[142:145], v[220:223], v[72:75]
	v_mfma_f32_16x16x32_bf16 v[118:121], v[146:149], v[178:181], v[118:121]
	v_mfma_f32_16x16x32_bf16 v[114:117], v[170:173], v[178:181], v[114:117]
	v_mfma_f32_16x16x32_bf16 v[102:105], v[146:149], v[196:199], v[102:105]
	v_mfma_f32_16x16x32_bf16 v[98:101], v[170:173], v[196:199], v[98:101]
	v_mfma_f32_16x16x32_bf16 v[86:89], v[146:149], v[208:211], v[86:89]
	v_mfma_f32_16x16x32_bf16 v[82:85], v[170:173], v[208:211], v[82:85]
	v_mfma_f32_16x16x32_bf16 v[68:71], v[146:149], v[216:219], v[68:71]
	v_mfma_f32_16x16x32_bf16 v[64:67], v[170:173], v[216:219], v[64:67]
	v_mfma_f32_16x16x32_bf16 v[118:121], v[150:153], v[182:185], v[118:121]
	v_mfma_f32_16x16x32_bf16 v[114:117], v[174:177], v[182:185], v[114:117]
	v_mfma_f32_16x16x32_bf16 v[102:105], v[150:153], v[204:207], v[102:105]
	v_mfma_f32_16x16x32_bf16 v[98:101], v[174:177], v[204:207], v[98:101]
	v_mfma_f32_16x16x32_bf16 v[86:89], v[150:153], v[212:215], v[86:89]
	v_mfma_f32_16x16x32_bf16 v[82:85], v[174:177], v[212:215], v[82:85]
	v_mfma_f32_16x16x32_bf16 v[68:71], v[150:153], v[220:223], v[68:71]
	v_mfma_f32_16x16x32_bf16 v[64:67], v[174:177], v[220:223], v[64:67]
	s_barrier
; #define PG8_STAGE(bufoff, gbase, voff) do { _Pragma("unroll") for (int _i = 0; _i < 2; ++_i) \
;         __builtin_amdgcn_global_load_lds((const unsigned*)((const char*)(gbase) + (voff)[_i]), (PG8_LAS unsigned*)(lds + (bufoff) + ldsw + _i * 8192), 16, 0, 0); } while (0)
; #define PG8_LDA(dst, b, h) do { _Pragma("unroll") for (int m = 0; m < 4; ++m) _Pragma("unroll") for (int k = 0; k < 2; ++k) dst[m][k] = *(const PG8_LAS bf16x8*)(lds + PG8_SA(b, h) + aoff + m * 2048 + k * 1024); } while (0)
; #define PG8_MMA(ai, bj, At, Bt) do { __builtin_amdgcn_s_setprio(1); _Pragma("unroll") for (int m = 0; m < 4; ++m) _Pragma("unroll") for (int n = 0; n < 2; ++n) _Pragma("unroll") for (int k = 0; k < 2; ++k) \
;         acc[ai][bj][m][n] = __builtin_amdgcn_mfma_f32_16x16x32_bf16(Bt[n][k], At[m][k], acc[ai][bj][m][n], 0, 0, 0); __builtin_amdgcn_s_setprio(0); } while (0)
; #define PG8_WAIT_V(n) asm volatile("s_waitcnt vmcnt(" #n ")" ::: "memory")
; #define PG8_WAIT_L(n) asm volatile("s_waitcnt lgkmcnt(" #n ")" ::: "memory")
; #define PG8_BAR __builtin_amdgcn_s_barrier()
; #define PG8_SCHED __builtin_amdgcn_sched_barrier(0)
; template <class Epi, class Sched, bool ALIGN_EPI = false, bool SP2 = false, bool HALFM = false>
; __device__ __forceinline__ void gemm_phase(PG8_LAS unsigned char* lds, const Gemm g, const Sched& S, const Epi& E) {
;     ...
;             if constexpr (!HALFM) PG8_LDA(At, 1, 1); PG8_STAGE(PG8_SB(1, 0), b3, voffB); PG8_STAGE(PG8_SB(1, 1), b3 + hstep, voffB); PG8_STAGE(PG8_SA(1, 0), a3, voffA);
;             PG8_WAIT_V(8); PG8_WAIT_L(0); PG8_BAR; if constexpr (!HALFM) { PG8_MMA(1, 0, At, B0); PG8_MMA(1, 1, At, B1); } PG8_BAR; PG8_SCHED;
;     ...
;         if (!has_next) break;
	s_add_i32 s22, s57, s26
	v_lshl_add_u64 v[186:187], v[186:187], 0, s[82:83]
	s_mov_b32 m0, s22
	ds_read_b128 v[178:181], v203 offset:49152
	ds_read_b128 v[182:185], v203 offset:50176
	ds_read_b128 v[196:199], v203 offset:51200
	ds_read_b128 v[204:207], v203 offset:52224
	ds_read_b128 v[208:211], v203 offset:53248
	ds_read_b128 v[212:215], v203 offset:54272
	ds_read_b128 v[216:219], v203 offset:55296
	ds_read_b128 v[220:223], v203 offset:56320
	global_load_lds_dwordx4 v[186:187], off
	s_add_i32 m0, s22, 0x2000
	s_add_u32 s20, s20, 0x40080
	v_lshl_add_u64 v[186:187], v[224:225], 0, s[82:83]
	s_addc_u32 s21, s21, 0
	s_add_i32 s22, s58, s26
	global_load_lds_dwordx4 v[186:187], off
	v_lshl_add_u64 v[186:187], s[20:21], 0, v[80:81]
	s_mov_b32 m0, s22
	s_nop 0
	global_load_lds_dwordx4 v[186:187], off
	v_lshl_add_u64 v[186:187], s[20:21], 0, v[160:161]
	s_add_i32 m0, s22, 0x2000
	s_nop 0
	global_load_lds_dwordx4 v[186:187], off
	v_lshl_add_u64 v[186:187], v[226:227], 0, s[82:83]
	s_mov_b32 m0, s47
	s_nop 0
	global_load_lds_dwordx4 v[186:187], off
	v_lshl_add_u64 v[186:187], v[228:229], 0, s[82:83]
	s_mov_b32 m0, s48
	s_nop 0
	global_load_lds_dwordx4 v[186:187], off
	s_waitcnt vmcnt(8)
	s_waitcnt lgkmcnt(0)
	s_barrier
	v_mfma_f32_16x16x32_bf16 v[60:63], v[130:133], v[178:181], v[60:63]
	v_mfma_f32_16x16x32_bf16 v[56:59], v[138:141], v[178:181], v[56:59]
	v_mfma_f32_16x16x32_bf16 v[44:47], v[130:133], v[196:199], v[44:47]
	v_mfma_f32_16x16x32_bf16 v[40:43], v[138:141], v[196:199], v[40:43]
	v_mfma_f32_16x16x32_bf16 v[28:31], v[130:133], v[208:211], v[28:31]
	v_mfma_f32_16x16x32_bf16 v[24:27], v[138:141], v[208:211], v[24:27]
	v_mfma_f32_16x16x32_bf16 v[12:15], v[130:133], v[216:219], v[12:15]
	v_mfma_f32_16x16x32_bf16 v[8:11], v[138:141], v[216:219], v[8:11]
	v_mfma_f32_16x16x32_bf16 v[60:63], v[134:137], v[182:185], v[60:63]
	v_mfma_f32_16x16x32_bf16 v[56:59], v[142:145], v[182:185], v[56:59]
	v_mfma_f32_16x16x32_bf16 v[44:47], v[134:137], v[204:207], v[44:47]
	v_mfma_f32_16x16x32_bf16 v[40:43], v[142:145], v[204:207], v[40:43]
	v_mfma_f32_16x16x32_bf16 v[28:31], v[134:137], v[212:215], v[28:31]
	v_mfma_f32_16x16x32_bf16 v[24:27], v[142:145], v[212:215], v[24:27]
	v_mfma_f32_16x16x32_bf16 v[12:15], v[134:137], v[220:223], v[12:15]
	v_mfma_f32_16x16x32_bf16 v[8:11], v[142:145], v[220:223], v[8:11]
	v_mfma_f32_16x16x32_bf16 v[52:55], v[146:149], v[178:181], v[52:55]
	v_mfma_f32_16x16x32_bf16 v[48:51], v[170:173], v[178:181], v[48:51]
	v_mfma_f32_16x16x32_bf16 v[36:39], v[146:149], v[196:199], v[36:39]
	v_mfma_f32_16x16x32_bf16 v[32:35], v[170:173], v[196:199], v[32:35]
	v_mfma_f32_16x16x32_bf16 v[20:23], v[146:149], v[208:211], v[20:23]
	v_mfma_f32_16x16x32_bf16 v[16:19], v[170:173], v[208:211], v[16:19]
	v_mfma_f32_16x16x32_bf16 v[4:7], v[146:149], v[216:219], v[4:7]
	v_mfma_f32_16x16x32_bf16 v[0:3], v[170:173], v[216:219], v[0:3]
	v_mfma_f32_16x16x32_bf16 v[52:55], v[150:153], v[182:185], v[52:55]
	v_mfma_f32_16x16x32_bf16 v[48:51], v[174:177], v[182:185], v[48:51]
	v_mfma_f32_16x16x32_bf16 v[36:39], v[150:153], v[204:207], v[36:39]
	v_mfma_f32_16x16x32_bf16 v[32:35], v[174:177], v[204:207], v[32:35]
	v_mfma_f32_16x16x32_bf16 v[20:23], v[150:153], v[212:215], v[20:23]
	v_mfma_f32_16x16x32_bf16 v[16:19], v[174:177], v[212:215], v[16:19]
	v_mfma_f32_16x16x32_bf16 v[4:7], v[150:153], v[220:223], v[4:7]
	v_mfma_f32_16x16x32_bf16 v[0:3], v[174:177], v[220:223], v[0:3]
	s_barrier
	s_add_i32 s56, s56, 2
	s_add_u32 s18, s18, 0x100
	s_addc_u32 s19, s19, 0
	s_add_u32 s54, s54, 0x100
	s_addc_u32 s55, s55, 0
	s_cmp_gt_u32 s56, 13
	s_cbranch_scc0 .LBB0_1165
	s_and_b64 vcc, exec, s[8:9]
	s_cbranch_vccz .LBB0_1168
	s_barrier
